# k22: attention 8-wave ping-pong: waves 4-7 staggered one barrier behind waves 0-3 (B2 restored, K/V LDS writes moved after B2)
# baseline (speedup 1.0000x reference)
; __device__ __forceinline__ int opaque_tid() { int t = threadIdx.x; asm volatile("" : "+v"(t)); return t; }
; __device__ __forceinline__ void attn_body(const bf16_t* Qb, const bf16_t* Kh, const bf16_t* Vh, const bf16_t* Gb, bf16_t* Ob, int seq, char* lds,
;                                           const float* qgain, const float* cosA, const float* sinA, int t0) {
;   const int tid = opaque_tid(), wid = tid >> 6, lane = tid & 63, r32 = lane & 31, hi = lane >> 5;
;   char* V_lds = lds; char* K_lds = lds + 2 * SHM_V;
;   float* ws = (float*)(lds + 2 * SHM_V + 2 * SHM_K) + wid * 64; float* li_l = ws; float* al_l = ws + 32;
;   float m_reg = -1e30f, l_reg = 0; f32x16 o[4] = {}; bf16x8 qr[8];
;   const bf16_t* Qw = Qb + (long)(wid * QBLK + r32) * LDQ + hi * 8;
; #pragma unroll
;   for (int d0 = 0; d0 < 8; ++d0) qr[d0] = ld8(Qw + d0 * 16);
;   {
;     float ss = 0.f;
; #pragma unroll
;     for (int d0 = 0; d0 < 8; ++d0)
; #pragma unroll
;       for (int e = 0; e < 8; ++e) { const float v = bf2f((unsigned short)qr[d0][e]); ss += v * v; }
;     { auto rr = __builtin_amdgcn_permlane32_swap(__float_as_uint(ss), __float_as_uint(ss), false, false); ss = __uint_as_float(rr[0]) + __uint_as_float(rr[1]); }
;     const float rinv = __builtin_amdgcn_rsqf(ss * (1.f / 128) + RMS_EPS);
.LBB0_258:
	s_lshl_b32 s14, s46, 6
	s_and_b32 s20, s14, 0x300
	s_lshl_b32 s14, s48, 4
	s_and_b32 s38, s47, 0xfffff000
	s_and_b32 s15, s14, 0xfffff000
	s_ashr_i32 s39, s38, 31
	s_mul_i32 s16, s15, 0x2800
	s_mul_hi_i32 s14, s15, 0x2800
	s_add_u32 s19, s4, s16
	s_addc_u32 s21, s5, s14
	s_lshl_b32 s14, s48, 5
	s_and_b32 s17, s14, 0xf00
	s_mul_i32 s14, s17, 0x2800
	s_add_u32 s16, s19, s14
	s_addc_u32 s14, s21, 0
	s_lshl_b32 s18, s48, 8
	s_and_b32 s18, s18, 0x700
	s_and_b32 s22, s48, 0x80
	s_or_b32 s18, s18, s22
	s_lshl_b32 s22, s18, 1
	v_mov_b32_e32 v94, v252
	s_add_u32 s22, s16, s22
	s_addc_u32 s23, s14, 0
	v_ashrrev_i32_e32 v179, 6, v94
	v_and_b32_e32 v181, 31, v94
	v_lshlrev_b32_e32 v178, 5, v179
	v_bfe_u32 v184, v94, 5, 1
	v_or_b32_e32 v95, v178, v181
	v_mov_b64_e32 v[0:1], s[22:23]
	v_mad_i64_i32 v[0:1], s[22:23], v95, s72, v[0:1]
	v_lshlrev_b32_e32 v176, 4, v184
	v_lshl_add_u64 v[4:5], v[0:1], 0, v[176:177]
	s_waitcnt vmcnt(4)
	v_and_b32_e32 v38, 32, v94
	global_load_dwordx4 v[46:49], v[4:5], off offset:224
	global_load_dwordx4 v[54:57], v[4:5], off offset:160
	global_load_dwordx4 v[62:65], v[4:5], off offset:192
	global_load_dwordx4 v[66:69], v[4:5], off offset:128
	global_load_dwordx4 v[8:11], v38, s[40:41] offset:16
	global_load_dwordx4 v[0:3], v38, s[40:41] offset:144
	global_load_dwordx4 v[96:99], v[4:5], off offset:64
	global_load_dwordx4 v[80:83], v[4:5], off offset:96
	global_load_dwordx4 v[100:103], v[4:5], off
	global_load_dwordx4 v[104:107], v[4:5], off offset:32
	v_or_b32_e32 v6, s17, v181
	v_add_u32_e32 v6, v6, v178
	v_ashrrev_i32_e32 v6, 1, v6
	v_and_b32_e32 v6, 0xffffffe0, v6
	v_ashrrev_i32_e32 v7, 31, v6
	v_lshlrev_b64 v[4:5], 2, v[6:7]
	v_mov_b32_e32 v39, v177
	v_lshl_add_u64 v[6:7], s[98:99], 0, v[4:5]
	v_lshl_add_u64 v[4:5], s[24:25], 0, v[4:5]
	v_lshl_add_u64 v[72:73], v[4:5], 0, v[38:39]
	v_lshl_add_u64 v[70:71], v[6:7], 0, v[38:39]
	global_load_dwordx4 v[4:7], v[72:73], off offset:16
	global_load_dwordx4 v[12:15], v[70:71], off offset:16
	global_load_dwordx4 v[28:31], v38, s[40:41]
	global_load_dwordx4 v[24:27], v38, s[40:41] offset:128
	global_load_dwordx4 v[20:23], v[72:73], off
	global_load_dwordx4 v[16:19], v[70:71], off
	s_lshl_b32 s22, s48, 7
	s_and_b32 s22, s22, 0x300
	s_add_u32 s19, s19, s22
	s_addc_u32 s21, s21, 0
	s_add_u32 s36, s19, 0x1000
	s_addc_u32 s37, s21, 0
	s_add_u32 s42, s19, 0x1400
	s_addc_u32 s43, s21, 0
	v_lshlrev_b32_e32 v185, 4, v94
	v_and_b32_e32 v186, 63, v94
	s_add_i32 s19, 0, 0x10000
	s_cmp_lg_u32 0, -1
	s_cselect_b32 s21, 0, 0
	s_mov_b32 s72, s73
	s_mov_b32 s74, s73
	s_mov_b32 s75, s73
	s_mov_b32 s76, s73
	s_mov_b32 s77, s73
	s_mov_b32 s78, s73
	s_mov_b32 s79, s73
	s_mov_b32 s80, s73
	s_mov_b32 s81, s73
	s_mov_b32 s82, s73
	s_mov_b32 s83, s73
	s_mov_b32 s84, s73
	s_mov_b32 s85, s73
	s_mov_b32 s86, s73
	s_mov_b32 s87, s73
	v_mov_b32_e32 v189, 0
	s_waitcnt vmcnt(15)
	v_lshlrev_b32_e32 v35, 16, v49
	v_and_b32_e32 v33, 0xffff0000, v49
	v_lshlrev_b32_e32 v41, 16, v48
	s_waitcnt vmcnt(12)
	v_lshlrev_b32_e32 v52, 16, v69
	s_waitcnt vmcnt(9)
	v_and_b32_e32 v119, 0xffff0000, v97
	s_waitcnt vmcnt(7)
	v_lshlrev_b32_e32 v84, 16, v103
	v_and_b32_e32 v86, 0xffff0000, v103
	v_lshlrev_b32_e32 v103, 16, v97
	v_lshlrev_b32_e32 v121, 16, v96
	v_and_b32_e32 v97, 0xffff0000, v96
	v_and_b32_e32 v96, 0xffff0000, v100
	v_and_b32_e32 v50, 0xffff0000, v69
	v_lshlrev_b32_e32 v60, 16, v67
	v_and_b32_e32 v58, 0xffff0000, v67
	v_lshlrev_b32_e32 v69, 16, v83
	v_and_b32_e32 v67, 0xffff0000, v83
	v_lshlrev_b32_e32 v85, 16, v99
	v_mov_b32_e32 v91, v2
	v_and_b32_e32 v87, 0xffff0000, v99
	v_mov_b32_e32 v2, v11
	v_lshlrev_b32_e32 v75, 16, v82
	v_and_b32_e32 v11, 0xffff0000, v82
	v_lshlrev_b32_e32 v79, 16, v81
	s_waitcnt vmcnt(6)
	v_lshlrev_b32_e32 v78, 16, v105
	v_and_b32_e32 v77, 0xffff0000, v81
	v_and_b32_e32 v76, 0xffff0000, v105
	v_lshlrev_b32_e32 v83, 16, v80
	v_lshlrev_b32_e32 v82, 16, v104
	v_and_b32_e32 v81, 0xffff0000, v80
	v_and_b32_e32 v80, 0xffff0000, v104
	v_lshlrev_b32_e32 v105, 16, v98
	v_lshlrev_b32_e32 v104, 16, v102
	v_and_b32_e32 v99, 0xffff0000, v98
	v_and_b32_e32 v98, 0xffff0000, v102
	v_lshlrev_b32_e32 v102, 16, v101
	v_and_b32_e32 v118, 0xffff0000, v101
	v_lshlrev_b32_e32 v120, 16, v100
	v_pk_mul_f32 v[100:101], v[96:97], v[96:97]
	v_lshlrev_b32_e32 v74, 16, v106
	v_pk_fma_f32 v[124:125], v[120:121], v[120:121], v[100:101]
	v_mov_b32_e32 v90, v10
	v_pk_fma_f32 v[124:125], v[102:103], v[102:103], v[124:125]
	v_and_b32_e32 v10, 0xffff0000, v106
	v_pk_fma_f32 v[124:125], v[118:119], v[118:119], v[124:125]
	v_lshlrev_b32_e32 v40, 16, v56
	v_pk_fma_f32 v[124:125], v[104:105], v[104:105], v[124:125]
	v_and_b32_e32 v37, 0xffff0000, v48
	v_pk_fma_f32 v[124:125], v[98:99], v[98:99], v[124:125]
	v_and_b32_e32 v36, 0xffff0000, v56
	v_pk_fma_f32 v[124:125], v[84:85], v[84:85], v[124:125]
	v_lshlrev_b32_e32 v45, 16, v47
	v_pk_fma_f32 v[124:125], v[86:87], v[86:87], v[124:125]
	v_and_b32_e32 v43, 0xffff0000, v47
	v_pk_fma_f32 v[124:125], v[82:83], v[82:83], v[124:125]
	v_lshlrev_b32_e32 v49, 16, v46
	v_pk_fma_f32 v[124:125], v[80:81], v[80:81], v[124:125]
	v_lshlrev_b32_e32 v48, 16, v54
	v_pk_fma_f32 v[124:125], v[78:79], v[78:79], v[124:125]
	v_and_b32_e32 v47, 0xffff0000, v46
	v_pk_fma_f32 v[124:125], v[76:77], v[76:77], v[124:125]
	v_and_b32_e32 v46, 0xffff0000, v54
	v_pk_fma_f32 v[124:125], v[74:75], v[74:75], v[124:125]
	v_lshlrev_b32_e32 v56, 16, v68
	v_and_b32_e32 v54, 0xffff0000, v68
	v_lshlrev_b32_e32 v68, 16, v107
	v_pk_fma_f32 v[124:125], v[10:11], v[10:11], v[124:125]
	v_lshlrev_b32_e32 v34, 16, v57
	v_and_b32_e32 v32, 0xffff0000, v57
	v_lshlrev_b32_e32 v53, 16, v65
	v_and_b32_e32 v51, 0xffff0000, v65
; __device__ __forceinline__ void attn_body(const bf16_t* Qb, const bf16_t* Kh, const bf16_t* Vh, const bf16_t* Gb, bf16_t* Ob, int seq, char* lds,
;                                           const float* qgain, const float* cosA, const float* sinA, int t0) {
;     ...
;     float ss = 0.f;
; #pragma unroll
;     for (int d0 = 0; d0 < 8; ++d0)
; #pragma unroll
;       for (int e = 0; e < 8; ++e) { const float v = bf2f((unsigned short)qr[d0][e]); ss += v * v; }
;     { auto rr = __builtin_amdgcn_permlane32_swap(__float_as_uint(ss), __float_as_uint(ss), false, false); ss = __uint_as_float(rr[0]) + __uint_as_float(rr[1]); }
;     const float rinv = __builtin_amdgcn_rsqf(ss * (1.f / 128) + RMS_EPS);
;     const int t = t0 + wid * QBLK + r32, rp = t >> 6, cp = t & 63;
; #pragma unroll
;     for (int half = 0; half < 2; ++half) { const int pos = half ? cp : rp;
; #pragma unroll
;       for (int dd = 0; dd < 2; ++dd) { const int dx = 4 * half + dd, dy = dx + 2, i0 = 16 * dd + 8 * hi;
;         const f32x4 c0 = *(const f32x4*)(cosA + pos * 32 + i0), c1 = *(const f32x4*)(cosA + pos * 32 + i0 + 4), s0 = *(const f32x4*)(sinA + pos * 32 + i0), s1 = *(const f32x4*)(sinA + pos * 32 + i0 + 4);
;         const f32x4 gx0 = *(const f32x4*)(qgain + 16 * dx + 8 * hi), gx1 = *(const f32x4*)(qgain + 16 * dx + 8 * hi + 4), gy0 = *(const f32x4*)(qgain + 16 * dy + 8 * hi), gy1 = *(const f32x4*)(qgain + 16 * dy + 8 * hi + 4);
;         float xo[8], yo[8];
; #pragma unroll
;         for (int e = 0; e < 8; ++e) { const float cc = e < 4 ? c0[e & 3] : c1[e & 3], sn = e < 4 ? s0[e & 3] : s1[e & 3];
;           const float x = bf2f((unsigned short)qr[dx][e]) * rinv * (e < 4 ? gx0[e & 3] : gx1[e & 3]), y = bf2f((unsigned short)qr[dy][e]) * rinv * (e < 4 ? gy0[e & 3] : gy1[e & 3]);
	v_lshlrev_b32_e32 v44, 16, v55
	v_and_b32_e32 v42, 0xffff0000, v55
	v_lshlrev_b32_e32 v57, 16, v64
	v_and_b32_e32 v55, 0xffff0000, v64
	v_lshlrev_b32_e32 v61, 16, v63
	v_and_b32_e32 v59, 0xffff0000, v63
	v_lshlrev_b32_e32 v65, 16, v62
	v_lshlrev_b32_e32 v64, 16, v66
	v_and_b32_e32 v63, 0xffff0000, v62
	v_and_b32_e32 v62, 0xffff0000, v66
	v_and_b32_e32 v66, 0xffff0000, v107
	v_pk_fma_f32 v[124:125], v[68:69], v[68:69], v[124:125]
	v_mov_b32_e32 v107, v0
	v_pk_fma_f32 v[124:125], v[66:67], v[66:67], v[124:125]
	v_mul_f32_e32 v0, v121, v121
	v_pk_add_f32 v[124:125], v[0:1], v[124:125] op_sel_hi:[0,1]
	v_pk_add_f32 v[100:101], v[100:101], v[124:125] op_sel:[1,0] op_sel_hi:[0,1]
	v_mul_f32_e32 v0, v103, v103
	v_pk_add_f32 v[100:101], v[0:1], v[100:101] op_sel_hi:[0,1]
	v_mul_f32_e32 v0, v119, v119
	v_pk_add_f32 v[100:101], v[0:1], v[100:101] op_sel_hi:[0,1]
	v_mul_f32_e32 v0, v105, v105
	v_pk_add_f32 v[100:101], v[0:1], v[100:101] op_sel_hi:[0,1]
	v_mul_f32_e32 v0, v99, v99
	v_pk_add_f32 v[100:101], v[0:1], v[100:101] op_sel_hi:[0,1]
	v_mul_f32_e32 v0, v85, v85
	v_pk_add_f32 v[100:101], v[0:1], v[100:101] op_sel_hi:[0,1]
	v_mul_f32_e32 v0, v87, v87
	v_pk_add_f32 v[100:101], v[0:1], v[100:101] op_sel_hi:[0,1]
	v_mul_f32_e32 v0, v83, v83
	v_pk_add_f32 v[100:101], v[0:1], v[100:101] op_sel_hi:[0,1]
	v_mul_f32_e32 v0, v81, v81
	v_pk_add_f32 v[100:101], v[0:1], v[100:101] op_sel_hi:[0,1]
	v_mul_f32_e32 v0, v79, v79
	v_pk_add_f32 v[100:101], v[0:1], v[100:101] op_sel_hi:[0,1]
	v_mul_f32_e32 v0, v77, v77
	v_pk_add_f32 v[100:101], v[0:1], v[100:101] op_sel_hi:[0,1]
	v_mul_f32_e32 v0, v75, v75
	v_pk_add_f32 v[100:101], v[0:1], v[100:101] op_sel_hi:[0,1]
	v_mul_f32_e32 v0, v11, v11
	v_pk_add_f32 v[100:101], v[0:1], v[100:101] op_sel_hi:[0,1]
	v_mul_f32_e32 v0, v69, v69
	v_pk_add_f32 v[100:101], v[0:1], v[100:101] op_sel_hi:[0,1]
	v_mul_f32_e32 v0, v67, v67
	v_pk_add_f32 v[100:101], v[0:1], v[100:101] op_sel_hi:[0,1]
	v_pk_fma_f32 v[100:101], v[64:65], v[64:65], v[100:101]
	v_mul_f32_e32 v0, v65, v65
	v_pk_fma_f32 v[100:101], v[62:63], v[62:63], v[100:101]
	v_mov_b32_e32 v110, v37
	v_pk_fma_f32 v[100:101], v[60:61], v[60:61], v[100:101]
	v_mov_b32_e32 v111, v41
	v_pk_fma_f32 v[100:101], v[58:59], v[58:59], v[100:101]
	v_mov_b32_e32 v108, v33
	v_pk_fma_f32 v[100:101], v[56:57], v[56:57], v[100:101]
	v_mov_b32_e32 v109, v35
	v_pk_fma_f32 v[100:101], v[54:55], v[54:55], v[100:101]
	v_mov_b32_e32 v106, v8
	v_pk_fma_f32 v[100:101], v[52:53], v[52:53], v[100:101]
	s_waitcnt vmcnt(2)
	v_mov_b32_e32 v123, v24
	v_pk_fma_f32 v[100:101], v[50:51], v[50:51], v[100:101]
	v_mov_b32_e32 v24, v29
	v_pk_fma_f32 v[100:101], v[48:49], v[48:49], v[100:101]
	v_mov_b32_e32 v114, v30
	v_pk_fma_f32 v[100:101], v[46:47], v[46:47], v[100:101]
	v_mov_b32_e32 v115, v26
	v_pk_fma_f32 v[100:101], v[44:45], v[44:45], v[100:101]
	v_mov_b32_e32 v122, v28
	v_pk_fma_f32 v[100:101], v[42:43], v[42:43], v[100:101]
	s_waitcnt vmcnt(1)
	v_mov_b32_e32 v116, v22
	v_pk_fma_f32 v[100:101], v[40:41], v[40:41], v[100:101]
	s_waitcnt vmcnt(0)
	v_mov_b32_e32 v117, v18
	v_pk_fma_f32 v[100:101], v[36:37], v[36:37], v[100:101]
	v_mov_b32_e32 v26, v31
	v_pk_fma_f32 v[100:101], v[34:35], v[34:35], v[100:101]
	v_mov_b32_e32 v112, v4
	v_pk_fma_f32 v[100:101], v[32:33], v[32:33], v[100:101]
	v_mov_b32_e32 v113, v12
	v_pk_add_f32 v[100:101], v[0:1], v[100:101] op_sel_hi:[0,1]
	v_mul_f32_e32 v0, v63, v63
	v_pk_add_f32 v[100:101], v[0:1], v[100:101] op_sel_hi:[0,1]
	v_mul_f32_e32 v0, v61, v61
	v_pk_add_f32 v[100:101], v[0:1], v[100:101] op_sel_hi:[0,1]
	v_mul_f32_e32 v0, v59, v59
	v_pk_add_f32 v[100:101], v[0:1], v[100:101] op_sel_hi:[0,1]
	v_mul_f32_e32 v0, v57, v57
	v_pk_add_f32 v[100:101], v[0:1], v[100:101] op_sel_hi:[0,1]
	v_mul_f32_e32 v0, v55, v55
	v_pk_add_f32 v[100:101], v[0:1], v[100:101] op_sel_hi:[0,1]
	v_mul_f32_e32 v0, v53, v53
	v_pk_add_f32 v[100:101], v[0:1], v[100:101] op_sel_hi:[0,1]
	v_mul_f32_e32 v0, v51, v51
	v_pk_add_f32 v[100:101], v[0:1], v[100:101] op_sel_hi:[0,1]
	v_mul_f32_e32 v0, v49, v49
	v_pk_add_f32 v[100:101], v[0:1], v[100:101] op_sel_hi:[0,1]
	v_mul_f32_e32 v0, v47, v47
	v_pk_add_f32 v[100:101], v[0:1], v[100:101] op_sel_hi:[0,1]
	v_mul_f32_e32 v0, v45, v45
	v_pk_add_f32 v[100:101], v[0:1], v[100:101] op_sel_hi:[0,1]
	v_mul_f32_e32 v0, v43, v43
	v_pk_add_f32 v[100:101], v[0:1], v[100:101] op_sel_hi:[0,1]
	v_mul_f32_e32 v0, v41, v41
	v_pk_add_f32 v[100:101], v[0:1], v[100:101] op_sel_hi:[0,1]
	v_pk_fma_f32 v[100:101], v[110:111], v[110:111], v[100:101]
	v_mul_f32_e32 v0, v35, v35
	v_pk_add_f32 v[100:101], v[0:1], v[100:101] op_sel_hi:[0,1]
	v_pk_fma_f32 v[100:101], v[108:109], v[108:109], v[100:101]
	v_mov_b32_e32 v110, v16
	v_mov_b32_e32 v0, v100
	s_nop 1
	v_permlane32_swap_b32_e32 v100, v0
	v_add_f32_e32 v0, v100, v0
	v_fmamk_f32 v0, v0, 0x3c000000, v244
	v_rsq_f32_e32 v8, v0
	v_mov_b32_e32 v101, v16
	v_mov_b32_e32 v16, v21
	v_mov_b32_e32 v100, v20
	v_pk_mul_f32 v[96:97], v[8:9], v[96:97] op_sel_hi:[0,1]
	v_pk_mul_f32 v[24:25], v[24:25], v[96:97]
	v_mov_b32_e32 v111, v20
	v_mov_b32_e32 v20, v17
	v_pk_mul_f32 v[16:17], v[16:17], v[24:25]
	v_pk_mul_f32 v[28:29], v[20:21], v[24:25]
	v_add_f32_e32 v24, v16, v17
	v_pk_mul_f32 v[16:17], v[8:9], v[102:103] op_sel_hi:[0,1]
	v_pk_mul_f32 v[16:17], v[114:115], v[16:17]
	v_mov_b32_e32 v20, v18
	v_mov_b32_e32 v21, v22
	v_pk_mul_f32 v[20:21], v[20:21], v[16:17]
	v_pk_mul_f32 v[16:17], v[116:117], v[16:17]
	v_sub_f32_e32 v28, v28, v29
	v_add_f32_e32 v29, v16, v17
	v_pk_mul_f32 v[16:17], v[8:9], v[118:119] op_sel_hi:[0,1]
	v_pk_mul_f32 v[16:17], v[26:27], v[16:17]
	v_mov_b32_e32 v22, v19
	v_mov_b32_e32 v18, v23
	v_sub_f32_e32 v25, v20, v21
; __device__ __forceinline__ unsigned cvtpk(float lo, float hi) { unsigned r; asm volatile("v_cvt_pk_bf16_f32 %0, %1, %2" : "=v"(r) : "v"(lo), "v"(hi)); return r; }
; __device__ __forceinline__ unsigned cvtpk(float lo, float hi) { unsigned r; asm volatile("v_cvt_pk_bf16_f32 %0, %1, %2" : "=v"(r) : "v"(lo), "v"(hi)); return r; }
; __device__ __forceinline__ void attn_body(const bf16_t* Qb, const bf16_t* Kh, const bf16_t* Vh, const bf16_t* Gb, bf16_t* Ob, int seq, char* lds,
;                                           const float* qgain, const float* cosA, const float* sinA, int t0) {
;     ...
;     const int t = t0 + wid * QBLK + r32, rp = t >> 6, cp = t & 63;
; #pragma unroll
;     for (int half = 0; half < 2; ++half) { const int pos = half ? cp : rp;
; #pragma unroll
;       for (int dd = 0; dd < 2; ++dd) { const int dx = 4 * half + dd, dy = dx + 2, i0 = 16 * dd + 8 * hi;
;         const f32x4 c0 = *(const f32x4*)(cosA + pos * 32 + i0), c1 = *(const f32x4*)(cosA + pos * 32 + i0 + 4), s0 = *(const f32x4*)(sinA + pos * 32 + i0), s1 = *(const f32x4*)(sinA + pos * 32 + i0 + 4);
;         const f32x4 gx0 = *(const f32x4*)(qgain + 16 * dx + 8 * hi), gx1 = *(const f32x4*)(qgain + 16 * dx + 8 * hi + 4), gy0 = *(const f32x4*)(qgain + 16 * dy + 8 * hi), gy1 = *(const f32x4*)(qgain + 16 * dy + 8 * hi + 4);
;         float xo[8], yo[8];
; #pragma unroll
;         for (int e = 0; e < 8; ++e) { const float cc = e < 4 ? c0[e & 3] : c1[e & 3], sn = e < 4 ? s0[e & 3] : s1[e & 3];
;           const float x = bf2f((unsigned short)qr[dx][e]) * rinv * (e < 4 ? gx0[e & 3] : gx1[e & 3]), y = bf2f((unsigned short)qr[dy][e]) * rinv * (e < 4 ? gy0[e & 3] : gy1[e & 3]);
;           xo[e] = x * cc - y * sn; yo[e] = y * cc + x * sn; }
;         u32x4 wx = {cvtpk(xo[0], xo[1]), cvtpk(xo[2], xo[3]), cvtpk(xo[4], xo[5]), cvtpk(xo[6], xo[7])}, wy = {cvtpk(yo[0], yo[1]), cvtpk(yo[2], yo[3]), cvtpk(yo[4], yo[5]), cvtpk(yo[6], yo[7])};
;         qr[dx] = *reinterpret_cast<bf16x8*>(&wx); qr[dy] = *reinterpret_cast<bf16x8*>(&wy); } }
	v_pk_mul_f32 v[20:21], v[22:23], v[16:17]
	v_pk_mul_f32 v[16:17], v[18:19], v[16:17]
	v_sub_f32_e32 v20, v20, v21
	v_add_f32_e32 v21, v16, v17
	v_pk_mul_f32 v[16:17], v[8:9], v[104:105] op_sel_hi:[0,1]
	v_pk_mul_f32 v[16:17], v[16:17], v[106:107]
	v_mov_b32_e32 v18, v12
	v_mov_b32_e32 v19, v4
	v_pk_mul_f32 v[18:19], v[18:19], v[16:17]
	v_pk_mul_f32 v[16:17], v[112:113], v[16:17]
	v_sub_f32_e32 v18, v18, v19
	v_add_f32_e32 v19, v16, v17
	v_pk_mul_f32 v[16:17], v[8:9], v[98:99] op_sel_hi:[0,1]
	v_mov_b32_e32 v0, v9
	v_pk_mul_f32 v[0:1], v[16:17], v[0:1]
	v_mov_b32_e32 v4, v13
	v_pk_mul_f32 v[16:17], v[4:5], v[0:1]
	v_mov_b32_e32 v12, v5
	v_pk_mul_f32 v[108:109], v[8:9], v[120:121] op_sel_hi:[0,1]
	v_sub_f32_e32 v9, v16, v17
	v_pk_mul_f32 v[0:1], v[12:13], v[0:1]
	v_mov_b32_e32 v88, v6
	v_add_f32_e32 v12, v0, v1
	v_pk_mul_f32 v[0:1], v[8:9], v[84:85] op_sel_hi:[0,1]
	v_mov_b32_e32 v89, v14
	v_pk_mul_f32 v[0:1], v[0:1], v[90:91]
	v_mov_b32_e32 v4, v14
	v_mov_b32_e32 v5, v6
	v_pk_mul_f32 v[4:5], v[4:5], v[0:1]
	v_pk_mul_f32 v[0:1], v[88:89], v[0:1]
	v_sub_f32_e32 v4, v4, v5
	v_add_f32_e32 v5, v0, v1
	v_pk_mul_f32 v[0:1], v[8:9], v[86:87] op_sel_hi:[0,1]
	v_pk_mul_f32 v[108:109], v[122:123], v[108:109]
	v_pk_mul_f32 v[0:1], v[0:1], v[2:3]
	v_mov_b32_e32 v6, v15
	v_mov_b32_e32 v92, v7
	v_mov_b32_e32 v93, v15
	v_pk_mul_f32 v[110:111], v[110:111], v[108:109]
	v_pk_mul_f32 v[2:3], v[6:7], v[0:1]
	v_sub_f32_e32 v30, v110, v111
	v_pk_mul_f32 v[100:101], v[100:101], v[108:109]
	v_sub_f32_e32 v2, v2, v3
	v_pk_mul_f32 v[0:1], v[92:93], v[0:1]
	v_add_f32_e32 v108, v100, v101
	v_add_f32_e32 v0, v0, v1
	v_cvt_pk_bf16_f32 v100, v30, v28
	v_cvt_pk_bf16_f32 v101, v25, v20
	v_cvt_pk_bf16_f32 v102, v18, v9
	v_cvt_pk_bf16_f32 v103, v4, v2
	v_cvt_pk_bf16_f32 v96, v108, v24
	v_cvt_pk_bf16_f32 v97, v29, v21
	v_cvt_pk_bf16_f32 v98, v19, v12
	v_cvt_pk_bf16_f32 v99, v5, v0
	global_load_dwordx4 v[2:5], v38, s[40:41] offset:64
	global_load_dwordx4 v[12:15], v38, s[40:41] offset:192
	global_load_dwordx4 v[16:19], v[70:71], off offset:64
	global_load_dwordx4 v[20:23], v[72:73], off offset:64
	global_load_dwordx4 v[24:27], v38, s[40:41] offset:80
	global_load_dwordx4 v[28:31], v38, s[40:41] offset:208
	global_load_dwordx4 v[84:87], v[70:71], off offset:80
	s_nop 0
	global_load_dwordx4 v[70:73], v[72:73], off offset:80
	v_lshlrev_b32_e32 v0, 7, v95
	v_and_b32_e32 v0, 0x1f80, v0
	v_mov_b32_e32 v1, v177
	v_lshl_add_u64 v[6:7], s[98:99], 0, v[0:1]
	v_lshl_add_u64 v[88:89], s[24:25], 0, v[0:1]
	v_lshl_add_u64 v[0:1], v[6:7], 0, v[38:39]
	v_pk_mul_f32 v[6:7], v[8:9], v[82:83] op_sel_hi:[0,1]
	s_waitcnt vmcnt(7)
	v_mov_b32_e32 v82, v2
	s_waitcnt vmcnt(6)
	v_mov_b32_e32 v83, v12
	v_pk_mul_f32 v[6:7], v[6:7], v[82:83]
	s_waitcnt vmcnt(5)
	v_mov_b32_e32 v82, v16
	s_waitcnt vmcnt(4)
	v_mov_b32_e32 v83, v20
	v_pk_mul_f32 v[82:83], v[82:83], v[6:7]
	v_mov_b32_e32 v12, v3
	v_sub_f32_e32 v9, v82, v83
	v_mov_b32_e32 v82, v20
	v_mov_b32_e32 v83, v16
	v_pk_mul_f32 v[6:7], v[82:83], v[6:7]
	v_mov_b32_e32 v20, v17
	v_add_f32_e32 v82, v6, v7
	v_pk_mul_f32 v[6:7], v[8:9], v[80:81] op_sel_hi:[0,1]
	v_pk_mul_f32 v[2:3], v[6:7], v[12:13]
	v_mov_b32_e32 v16, v21
	v_pk_mul_f32 v[6:7], v[20:21], v[2:3]
	v_pk_mul_f32 v[2:3], v[16:17], v[2:3]
	v_sub_f32_e32 v12, v6, v7
	v_add_f32_e32 v13, v2, v3
	v_pk_mul_f32 v[2:3], v[8:9], v[78:79] op_sel_hi:[0,1]
	v_mov_b32_e32 v6, v4
	v_mov_b32_e32 v7, v14
	v_pk_mul_f32 v[2:3], v[2:3], v[6:7]
	v_mov_b32_e32 v6, v18
	v_mov_b32_e32 v7, v22
	v_pk_mul_f32 v[6:7], v[6:7], v[2:3]
	v_mov_b32_e32 v14, v5
	v_sub_f32_e32 v16, v6, v7
	v_mov_b32_e32 v6, v22
	v_mov_b32_e32 v7, v18
	v_pk_mul_f32 v[2:3], v[6:7], v[2:3]
	v_mov_b32_e32 v22, v19
	v_add_f32_e32 v6, v2, v3
	v_pk_mul_f32 v[2:3], v[8:9], v[76:77] op_sel_hi:[0,1]
	v_pk_mul_f32 v[2:3], v[2:3], v[14:15]
	v_mov_b32_e32 v18, v23
	v_pk_mul_f32 v[4:5], v[22:23], v[2:3]
	v_pk_mul_f32 v[2:3], v[18:19], v[2:3]
	v_sub_f32_e32 v7, v4, v5
	v_add_f32_e32 v14, v2, v3
	v_pk_mul_f32 v[2:3], v[8:9], v[74:75] op_sel_hi:[0,1]
	s_waitcnt vmcnt(3)
	v_mov_b32_e32 v4, v24
	s_waitcnt vmcnt(2)
	v_mov_b32_e32 v5, v28
	v_pk_mul_f32 v[2:3], v[2:3], v[4:5]
	s_waitcnt vmcnt(1)
	v_mov_b32_e32 v4, v84
	s_waitcnt vmcnt(0)
	v_mov_b32_e32 v5, v70
	v_pk_mul_f32 v[4:5], v[4:5], v[2:3]
	v_mov_b32_e32 v28, v25
	v_sub_f32_e32 v15, v4, v5
	v_mov_b32_e32 v4, v70
	v_mov_b32_e32 v5, v84
	v_pk_mul_f32 v[2:3], v[4:5], v[2:3]
	v_mov_b32_e32 v70, v85
	v_add_f32_e32 v17, v2, v3
	v_pk_mul_f32 v[2:3], v[8:9], v[10:11] op_sel_hi:[0,1]
	v_pk_mul_f32 v[2:3], v[2:3], v[28:29]
	v_mov_b32_e32 v84, v71
	v_pk_mul_f32 v[4:5], v[70:71], v[2:3]
	v_pk_mul_f32 v[2:3], v[84:85], v[2:3]
	v_sub_f32_e32 v10, v4, v5
	v_add_f32_e32 v11, v2, v3
	v_pk_mul_f32 v[2:3], v[8:9], v[68:69] op_sel_hi:[0,1]
	v_mov_b32_e32 v4, v26
	v_mov_b32_e32 v5, v30
	v_pk_mul_f32 v[2:3], v[2:3], v[4:5]
	v_mov_b32_e32 v4, v86
	v_mov_b32_e32 v5, v72
	v_pk_mul_f32 v[4:5], v[4:5], v[2:3]
	v_mov_b32_e32 v30, v27
	v_sub_f32_e32 v18, v4, v5
	v_mov_b32_e32 v4, v72
	v_mov_b32_e32 v5, v86
	v_pk_mul_f32 v[2:3], v[4:5], v[2:3]
	v_mov_b32_e32 v72, v87
	v_add_f32_e32 v19, v2, v3
	v_pk_mul_f32 v[2:3], v[8:9], v[66:67] op_sel_hi:[0,1]
	v_pk_mul_f32 v[2:3], v[2:3], v[30:31]
	v_mov_b32_e32 v86, v73
	v_pk_mul_f32 v[4:5], v[72:73], v[2:3]
	v_pk_mul_f32 v[2:3], v[86:87], v[2:3]
	v_sub_f32_e32 v4, v4, v5
	v_add_f32_e32 v2, v2, v3
	v_cvt_pk_bf16_f32 v108, v9, v12
	v_cvt_pk_bf16_f32 v109, v16, v7
	v_cvt_pk_bf16_f32 v110, v15, v10
	v_cvt_pk_bf16_f32 v111, v18, v4
	v_cvt_pk_bf16_f32 v104, v82, v13
	v_cvt_pk_bf16_f32 v105, v6, v14
	v_cvt_pk_bf16_f32 v106, v17, v11
	v_cvt_pk_bf16_f32 v107, v19, v2
	global_load_dwordx4 v[2:5], v38, s[40:41] offset:256
	global_load_dwordx4 v[10:13], v38, s[40:41] offset:384
	v_lshl_add_u64 v[6:7], v[88:89], 0, v[38:39]
	global_load_dwordx4 v[14:17], v[0:1], off
	global_load_dwordx4 v[18:21], v[6:7], off
	global_load_dwordx4 v[22:25], v38, s[40:41] offset:272
	global_load_dwordx4 v[26:29], v38, s[40:41] offset:400
	global_load_dwordx4 v[66:69], v[0:1], off offset:16
	global_load_dwordx4 v[70:73], v[6:7], off offset:16
	v_pk_mul_f32 v[30:31], v[8:9], v[64:65] op_sel_hi:[0,1]
	s_waitcnt vmcnt(7)
; __device__ __forceinline__ unsigned cvtpk(float lo, float hi) { unsigned r; asm volatile("v_cvt_pk_bf16_f32 %0, %1, %2" : "=v"(r) : "v"(lo), "v"(hi)); return r; }
; __device__ __forceinline__ int v_st(int k, int c) { const int kk = (k & ~0xC) | ((k & 4) << 1) | ((k & 8) >> 1); return ((kk >> 3) * 4 + (c >> 5)) * 512 + ((kk & 7) * 32 + (c & 31)) * 2; }
; __device__ __forceinline__ unsigned cvtpk(float lo, float hi) { unsigned r; asm volatile("v_cvt_pk_bf16_f32 %0, %1, %2" : "=v"(r) : "v"(lo), "v"(hi)); return r; }
; __device__ __forceinline__ void attn_body(const bf16_t* Qb, const bf16_t* Kh, const bf16_t* Vh, const bf16_t* Gb, bf16_t* Ob, int seq, char* lds,
;                                           const float* qgain, const float* cosA, const float* sinA, int t0) {
;     ...
;     const int t = t0 + wid * QBLK + r32, rp = t >> 6, cp = t & 63;
; #pragma unroll
;     for (int half = 0; half < 2; ++half) { const int pos = half ? cp : rp;
; #pragma unroll
;       for (int dd = 0; dd < 2; ++dd) { const int dx = 4 * half + dd, dy = dx + 2, i0 = 16 * dd + 8 * hi;
;         const f32x4 c0 = *(const f32x4*)(cosA + pos * 32 + i0), c1 = *(const f32x4*)(cosA + pos * 32 + i0 + 4), s0 = *(const f32x4*)(sinA + pos * 32 + i0), s1 = *(const f32x4*)(sinA + pos * 32 + i0 + 4);
;         const f32x4 gx0 = *(const f32x4*)(qgain + 16 * dx + 8 * hi), gx1 = *(const f32x4*)(qgain + 16 * dx + 8 * hi + 4), gy0 = *(const f32x4*)(qgain + 16 * dy + 8 * hi), gy1 = *(const f32x4*)(qgain + 16 * dy + 8 * hi + 4);
;         float xo[8], yo[8];
; #pragma unroll
;         for (int e = 0; e < 8; ++e) { const float cc = e < 4 ? c0[e & 3] : c1[e & 3], sn = e < 4 ? s0[e & 3] : s1[e & 3];
;           const float x = bf2f((unsigned short)qr[dx][e]) * rinv * (e < 4 ? gx0[e & 3] : gx1[e & 3]), y = bf2f((unsigned short)qr[dy][e]) * rinv * (e < 4 ? gy0[e & 3] : gy1[e & 3]);
;           xo[e] = x * cc - y * sn; yo[e] = y * cc + x * sn; }
;         u32x4 wx = {cvtpk(xo[0], xo[1]), cvtpk(xo[2], xo[3]), cvtpk(xo[4], xo[5]), cvtpk(xo[6], xo[7])}, wy = {cvtpk(yo[0], yo[1]), cvtpk(yo[2], yo[3]), cvtpk(yo[4], yo[5]), cvtpk(yo[6], yo[7])};
;         qr[dx] = *reinterpret_cast<bf16x8*>(&wx); qr[dy] = *reinterpret_cast<bf16x8*>(&wy); } }
;   }
;   const int sr = tid >> 4, sc = (tid & 15) * 8, vst0 = v_st(sr, sc), vst1 = v_st(32 + sr, sc);
	v_mov_b32_e32 v64, v2
	s_waitcnt vmcnt(6)
	v_mov_b32_e32 v65, v10
	v_pk_mul_f32 v[30:31], v[30:31], v[64:65]
	s_waitcnt vmcnt(5)
	v_mov_b32_e32 v64, v14
	s_waitcnt vmcnt(4)
	v_mov_b32_e32 v65, v18
	v_pk_mul_f32 v[64:65], v[64:65], v[30:31]
	v_mov_b32_e32 v10, v3
	v_sub_f32_e32 v9, v64, v65
	v_mov_b32_e32 v64, v18
	v_mov_b32_e32 v65, v14
	v_pk_mul_f32 v[30:31], v[64:65], v[30:31]
	v_mov_b32_e32 v18, v15
	v_add_f32_e32 v39, v30, v31
	v_pk_mul_f32 v[30:31], v[8:9], v[62:63] op_sel_hi:[0,1]
	v_pk_mul_f32 v[2:3], v[30:31], v[10:11]
	v_mov_b32_e32 v14, v19
	v_pk_mul_f32 v[10:11], v[18:19], v[2:3]
	v_pk_mul_f32 v[2:3], v[14:15], v[2:3]
	v_sub_f32_e32 v18, v10, v11
	v_add_f32_e32 v14, v2, v3
	v_pk_mul_f32 v[2:3], v[8:9], v[60:61] op_sel_hi:[0,1]
	v_mov_b32_e32 v10, v4
	v_mov_b32_e32 v11, v12
	v_pk_mul_f32 v[2:3], v[2:3], v[10:11]
	v_mov_b32_e32 v10, v16
	v_mov_b32_e32 v11, v20
	v_pk_mul_f32 v[10:11], v[10:11], v[2:3]
	v_mov_b32_e32 v12, v5
	v_sub_f32_e32 v15, v10, v11
	v_mov_b32_e32 v10, v20
	v_mov_b32_e32 v11, v16
	v_pk_mul_f32 v[2:3], v[10:11], v[2:3]
	v_mov_b32_e32 v20, v17
	v_add_f32_e32 v10, v2, v3
	v_pk_mul_f32 v[2:3], v[8:9], v[58:59] op_sel_hi:[0,1]
	v_pk_mul_f32 v[2:3], v[2:3], v[12:13]
	v_mov_b32_e32 v16, v21
	v_pk_mul_f32 v[4:5], v[20:21], v[2:3]
	v_pk_mul_f32 v[2:3], v[16:17], v[2:3]
	v_sub_f32_e32 v11, v4, v5
	v_add_f32_e32 v12, v2, v3
	v_pk_mul_f32 v[2:3], v[8:9], v[56:57] op_sel_hi:[0,1]
	s_waitcnt vmcnt(3)
	v_mov_b32_e32 v4, v22
	s_waitcnt vmcnt(2)
	v_mov_b32_e32 v5, v26
	v_pk_mul_f32 v[2:3], v[2:3], v[4:5]
	s_waitcnt vmcnt(1)
	v_mov_b32_e32 v4, v66
	s_waitcnt vmcnt(0)
	v_mov_b32_e32 v5, v70
	v_pk_mul_f32 v[4:5], v[4:5], v[2:3]
	v_mov_b32_e32 v26, v23
	v_sub_f32_e32 v13, v4, v5
	v_mov_b32_e32 v4, v70
	v_mov_b32_e32 v5, v66
	v_pk_mul_f32 v[2:3], v[4:5], v[2:3]
	v_mov_b32_e32 v70, v67
	v_add_f32_e32 v16, v2, v3
	v_pk_mul_f32 v[2:3], v[8:9], v[54:55] op_sel_hi:[0,1]
	v_pk_mul_f32 v[2:3], v[2:3], v[26:27]
	v_mov_b32_e32 v66, v71
	v_pk_mul_f32 v[4:5], v[70:71], v[2:3]
	v_pk_mul_f32 v[2:3], v[66:67], v[2:3]
	v_sub_f32_e32 v17, v4, v5
	v_add_f32_e32 v19, v2, v3
	v_pk_mul_f32 v[2:3], v[8:9], v[52:53] op_sel_hi:[0,1]
	v_mov_b32_e32 v4, v24
	v_mov_b32_e32 v5, v28
	v_pk_mul_f32 v[2:3], v[2:3], v[4:5]
	v_mov_b32_e32 v4, v68
	v_mov_b32_e32 v5, v72
	v_pk_mul_f32 v[4:5], v[4:5], v[2:3]
	v_mov_b32_e32 v28, v25
	v_sub_f32_e32 v20, v4, v5
	v_mov_b32_e32 v4, v72
	v_mov_b32_e32 v5, v68
	v_pk_mul_f32 v[2:3], v[4:5], v[2:3]
	v_mov_b32_e32 v72, v69
	v_add_f32_e32 v21, v2, v3
	v_pk_mul_f32 v[2:3], v[8:9], v[50:51] op_sel_hi:[0,1]
	v_pk_mul_f32 v[2:3], v[2:3], v[28:29]
	v_mov_b32_e32 v68, v73
	v_pk_mul_f32 v[4:5], v[72:73], v[2:3]
	v_pk_mul_f32 v[2:3], v[68:69], v[2:3]
	v_sub_f32_e32 v4, v4, v5
	v_add_f32_e32 v2, v2, v3
	v_cvt_pk_bf16_f32 v116, v9, v18
	v_cvt_pk_bf16_f32 v117, v15, v11
	v_cvt_pk_bf16_f32 v118, v13, v17
	v_cvt_pk_bf16_f32 v119, v20, v4
	v_cvt_pk_bf16_f32 v112, v39, v14
	v_cvt_pk_bf16_f32 v113, v10, v12
	v_cvt_pk_bf16_f32 v114, v16, v19
	v_cvt_pk_bf16_f32 v115, v21, v2
	global_load_dwordx4 v[2:5], v38, s[40:41] offset:320
	global_load_dwordx4 v[10:13], v38, s[40:41] offset:448
	global_load_dwordx4 v[14:17], v[0:1], off offset:64
	global_load_dwordx4 v[18:21], v[6:7], off offset:64
	global_load_dwordx4 v[22:25], v38, s[40:41] offset:336
	global_load_dwordx4 v[26:29], v38, s[40:41] offset:464
	global_load_dwordx4 v[50:53], v[0:1], off offset:80
	global_load_dwordx4 v[54:57], v[6:7], off offset:80
	v_pk_mul_f32 v[0:1], v[8:9], v[48:49] op_sel_hi:[0,1]
	v_ashrrev_i32_e32 v48, 4, v94
	v_add_u32_e32 v66, 0x80, v48
	v_mad_i64_i32 v[66:67], s[22:23], v66, s69, 0
	v_add_u32_e32 v70, 0xa0, v48
	v_mad_i64_i32 v[70:71], s[22:23], v70, s69, 0
	v_ashrrev_i32_e32 v49, 31, v48
	s_waitcnt vmcnt(7)
	v_mov_b32_e32 v6, v2
	s_waitcnt vmcnt(6)
	v_mov_b32_e32 v7, v10
	v_pk_mul_f32 v[0:1], v[0:1], v[6:7]
	s_waitcnt vmcnt(5)
	v_mov_b32_e32 v6, v14
	s_waitcnt vmcnt(4)
	v_mov_b32_e32 v7, v18
	v_pk_mul_f32 v[6:7], v[6:7], v[0:1]
	v_mov_b32_e32 v10, v3
	v_sub_f32_e32 v9, v6, v7
	v_mov_b32_e32 v6, v18
	v_mov_b32_e32 v7, v14
	v_pk_mul_f32 v[0:1], v[6:7], v[0:1]
	v_mov_b32_e32 v18, v15
	v_add_f32_e32 v6, v0, v1
	v_pk_mul_f32 v[0:1], v[8:9], v[46:47] op_sel_hi:[0,1]
	v_pk_mul_f32 v[0:1], v[0:1], v[10:11]
	v_mov_b32_e32 v14, v19
	v_pk_mul_f32 v[2:3], v[18:19], v[0:1]
	v_pk_mul_f32 v[0:1], v[14:15], v[0:1]
	v_sub_f32_e32 v7, v2, v3
	v_add_f32_e32 v10, v0, v1
	v_pk_mul_f32 v[0:1], v[8:9], v[44:45] op_sel_hi:[0,1]
	v_mov_b32_e32 v2, v4
	v_mov_b32_e32 v3, v12
	v_pk_mul_f32 v[0:1], v[0:1], v[2:3]
	v_mov_b32_e32 v2, v16
	v_mov_b32_e32 v3, v20
	v_pk_mul_f32 v[2:3], v[2:3], v[0:1]
	v_mov_b32_e32 v12, v5
	v_sub_f32_e32 v4, v2, v3
	v_mov_b32_e32 v2, v20
	v_mov_b32_e32 v3, v16
	v_pk_mul_f32 v[0:1], v[2:3], v[0:1]
	v_mov_b32_e32 v20, v17
	v_add_f32_e32 v11, v0, v1
	v_pk_mul_f32 v[0:1], v[8:9], v[42:43] op_sel_hi:[0,1]
	v_pk_mul_f32 v[0:1], v[0:1], v[12:13]
	v_mov_b32_e32 v16, v21
	v_pk_mul_f32 v[2:3], v[20:21], v[0:1]
	v_pk_mul_f32 v[0:1], v[16:17], v[0:1]
	v_sub_f32_e32 v5, v2, v3
	v_add_f32_e32 v12, v0, v1
	v_pk_mul_f32 v[0:1], v[8:9], v[40:41] op_sel_hi:[0,1]
	s_waitcnt vmcnt(3)
	v_mov_b32_e32 v2, v22
	s_waitcnt vmcnt(2)
	v_mov_b32_e32 v3, v26
	v_pk_mul_f32 v[0:1], v[0:1], v[2:3]
	s_waitcnt vmcnt(1)
	v_mov_b32_e32 v2, v50
	s_waitcnt vmcnt(0)
; __device__ __forceinline__ int v_st(int k, int c) { const int kk = (k & ~0xC) | ((k & 4) << 1) | ((k & 8) >> 1); return ((kk >> 3) * 4 + (c >> 5)) * 512 + ((kk & 7) * 32 + (c & 31)) * 2; }
; __device__ __forceinline__ int v_rd_base(int lane) { return ((lane & 3) << 3) | (((lane >> 2) & 3) << 6) | (((lane >> 4) & 1) << 5) | (((lane >> 5) & 1) << 8); }
; #define SLOAD(i, k0) do { sr_[i].vs0 = ld8(&Vh[(long)((k0) + sr) * LDK + sc]); sr_[i].vs1 = ld8(&Vh[(long)((k0) + 32 + sr) * LDK + sc]); \
;     sr_[i].ks0 = ld8(&Kh[(long)((k0) + sr) * LDK + sc]); sr_[i].ks1 = ld8(&Kh[(long)((k0) + 32 + sr) * LDK + sc]); } while (0)
; #define SWRITE(b, i) do { *(bf16x8*)(V_lds + (b) * SHM_V + vst0) = sr_[i].vs0;          \
;     *(bf16x8*)(V_lds + (b) * SHM_V + vst1) = sr_[i].vs1; int kc = sc * 2;               \
;     *(bf16x8*)(K_lds + (b) * SHM_K + KSWZ(sr, kc)) = sr_[i].ks0;                       \
;     *(bf16x8*)(K_lds + (b) * SHM_K + KSWZ(32 + sr, kc)) = sr_[i].ks1; } while (0)
; __device__ __forceinline__ void attn_body(const bf16_t* Qb, const bf16_t* Kh, const bf16_t* Vh, const bf16_t* Gb, bf16_t* Ob, int seq, char* lds,
;                                           const float* qgain, const float* cosA, const float* sinA, int t0) {
;     ...
;   const int sr = tid >> 4, sc = (tid & 15) * 8, vst0 = v_st(sr, sc), vst1 = v_st(32 + sr, sc);
;   const int vb0 = (int)(uintptr_t)V_lds + v_rd_base(lane);
;   struct { bf16x8 vs0, vs1, ks0, ks1; } sr_[2];
;     ...
;   f32x16 pA0, pA1, pB0, pB1; float mnA, mnB, alA, alB; bf16x8 pa0, pa1, pa2, pa3; const int NT = seq / KVBLK;
;   constexpr int SE = 0, SO = 1;
;   SLOAD(SE, 0); asm volatile("s_waitcnt vmcnt(0)" ::: "memory"); SWRITE(0, SE); __syncthreads();
;   qkt(pA0, pA1, K_lds, qr, r32, hi); partialSM(pA0, pA1, m_reg, mnA, alA);
	v_mov_b32_e32 v3, v54
	v_pk_mul_f32 v[2:3], v[2:3], v[0:1]
	v_mov_b32_e32 v26, v23
	v_sub_f32_e32 v13, v2, v3
	v_mov_b32_e32 v2, v54
	v_mov_b32_e32 v3, v50
	v_pk_mul_f32 v[0:1], v[2:3], v[0:1]
	v_mov_b32_e32 v54, v51
	v_add_f32_e32 v14, v0, v1
	v_pk_mul_f32 v[0:1], v[8:9], v[36:37] op_sel_hi:[0,1]
	v_pk_mul_f32 v[0:1], v[0:1], v[26:27]
	v_mov_b32_e32 v50, v55
	v_pk_mul_f32 v[2:3], v[54:55], v[0:1]
	v_pk_mul_f32 v[0:1], v[50:51], v[0:1]
	v_sub_f32_e32 v15, v2, v3
	v_add_f32_e32 v16, v0, v1
	v_pk_mul_f32 v[0:1], v[8:9], v[34:35] op_sel_hi:[0,1]
	v_mov_b32_e32 v2, v24
	v_mov_b32_e32 v3, v28
	v_pk_mul_f32 v[0:1], v[0:1], v[2:3]
	v_mov_b32_e32 v2, v52
	v_mov_b32_e32 v3, v56
	v_pk_mul_f32 v[2:3], v[2:3], v[0:1]
	v_mov_b32_e32 v28, v25
	v_sub_f32_e32 v17, v2, v3
	v_mov_b32_e32 v2, v56
	v_mov_b32_e32 v3, v52
	v_pk_mul_f32 v[0:1], v[2:3], v[0:1]
	v_mov_b32_e32 v56, v53
	v_add_f32_e32 v18, v0, v1
	v_pk_mul_f32 v[0:1], v[8:9], v[32:33] op_sel_hi:[0,1]
	v_pk_mul_f32 v[0:1], v[0:1], v[28:29]
	v_mov_b32_e32 v52, v57
	v_pk_mul_f32 v[2:3], v[56:57], v[0:1]
	v_pk_mul_f32 v[0:1], v[52:53], v[0:1]
	v_sub_f32_e32 v2, v2, v3
	v_add_f32_e32 v0, v0, v1
	v_cvt_pk_bf16_f32 v124, v9, v7
	v_cvt_pk_bf16_f32 v125, v4, v5
	v_cvt_pk_bf16_f32 v126, v13, v15
	v_cvt_pk_bf16_f32 v127, v17, v2
	v_cvt_pk_bf16_f32 v120, v6, v10
	v_cvt_pk_bf16_f32 v121, v11, v12
	v_cvt_pk_bf16_f32 v122, v14, v16
	v_lshlrev_b32_e32 v16, 3, v94
	v_cvt_pk_bf16_f32 v123, v18, v0
	v_and_b32_e32 v180, 0x78, v16
	v_mad_i64_i32 v[0:1], s[22:23], v48, s69, 0
	v_or_b32_e32 v0, v0, v180
	v_add_u32_e32 v17, 32, v48
	v_lshlrev_b64 v[8:9], 1, v[0:1]
	v_lshl_add_u64 v[0:1], s[42:43], 0, v[8:9]
	v_mad_i64_i32 v[4:5], s[22:23], v17, s69, 0
	global_load_dwordx4 v[0:3], v[0:1], off
	v_or_b32_e32 v4, v4, v180
	v_lshlrev_b64 v[12:13], 1, v[4:5]
	v_lshl_add_u64 v[4:5], s[42:43], 0, v[12:13]
	v_lshl_add_u64 v[8:9], s[36:37], 0, v[8:9]
	global_load_dwordx4 v[4:7], v[4:5], off
	v_lshl_add_u64 v[12:13], s[36:37], 0, v[12:13]
	global_load_dwordx4 v[8:11], v[8:9], off
	v_and_b32_e32 v18, 0xfffff0, v48
	global_load_dwordx4 v[12:15], v[12:13], off
	v_lshlrev_b32_e32 v19, 1, v48
	v_and_or_b32 v18, v19, 8, v18
	v_lshrrev_b32_e32 v19, 1, v48
	v_lshrrev_b32_e32 v18, 1, v18
	v_bfe_u32 v16, v16, 5, 2
	v_and_b32_e32 v20, 3, v48
	v_or_b32_e32 v18, v18, v16
	v_and_or_b32 v19, v19, 4, v20
	v_lshlrev_b32_e32 v20, 1, v180
	v_and_b32_e32 v22, 0xfffff0, v17
	v_lshlrev_b32_e32 v23, 1, v17
	v_lshlrev_b32_e32 v18, 9, v18
	v_lshlrev_b32_e32 v19, 6, v19
	v_and_b32_e32 v21, 48, v20
	v_and_or_b32 v22, v23, 8, v22
	v_or3_b32 v18, v18, v19, v21
	v_lshrrev_b32_e32 v22, 1, v22
	v_or_b32_e32 v16, v22, v16
	v_add_u32_e32 v192, 0, v18
	v_lshlrev_b32_e32 v16, 9, v16
	s_waitcnt vmcnt(0)
	v_or3_b32 v16, v16, v19, v21
	v_add_u32_e32 v193, 0, v16
	v_or_b32_e32 v66, v66, v180
	v_lshlrev_b64 v[66:67], 1, v[66:67]
	v_or_b32_e32 v70, v70, v180
	v_lshl_add_u64 v[68:69], s[42:43], 0, v[66:67]
	v_lshlrev_b64 v[70:71], 1, v[70:71]
	v_lshl_add_u64 v[66:67], s[36:37], 0, v[66:67]
	v_lshl_add_u64 v[72:73], s[42:43], 0, v[70:71]
	s_waitcnt vmcnt(3)
	ds_write_b128 v192, v[0:3]
	v_lshlrev_b32_e32 v0, 8, v48
	v_and_b32_e32 v1, 0x70, v94
	v_bitop3_b32 v0, v20, v0, v1 bitop3:0xde
	v_add_u32_e32 v199, 0, v0
	v_lshlrev_b32_e32 v0, 8, v17
	s_waitcnt vmcnt(2)
	ds_write_b128 v193, v[4:7]
	s_waitcnt vmcnt(1)
	ds_write_b128 v199, v[8:11] offset:32768
	v_bitop3_b32 v0, v20, v0, v1 bitop3:0xde
	v_lshlrev_b32_e32 v8, 8, v181
	v_and_b32_e32 v9, 0x70, v185
	v_add_u32_e32 v200, 0, v0
	v_bitop3_b32 v0, v176, v8, v9 bitop3:0xde
	v_add_u32_e32 v201, 0, v0
	s_waitcnt vmcnt(0)
	ds_write_b128 v200, v[12:15] offset:32768
	s_waitcnt lgkmcnt(0)
	s_barrier
	ds_read_b128 v[0:3], v201 offset:32768
	ds_read_b128 v[4:7], v201 offset:40960
	s_waitcnt lgkmcnt(1)
	v_mfma_f32_32x32x16_bf16 v[32:47], v[0:3], v[100:103], 0
	v_or_b32_e32 v0, 32, v176
	v_bitop3_b32 v0, v0, v8, v9 bitop3:0xde
	v_add_u32_e32 v204, 0, v0
	v_lshlrev_b32_e32 v10, 3, v186
	s_waitcnt lgkmcnt(0)
	v_mfma_f32_32x32x16_bf16 v[16:31], v[4:7], v[100:103], 0
	ds_read_b128 v[0:3], v204 offset:32768
	ds_read_b128 v[4:7], v204 offset:40960
	s_waitcnt lgkmcnt(1)
	v_mfma_f32_32x32x16_bf16 v[32:47], v[0:3], v[108:111], v[32:47]
	v_or_b32_e32 v0, 64, v176
	v_bitop3_b32 v0, v0, v8, v9 bitop3:0xde
	v_add_u32_e32 v205, 0, v0
	s_waitcnt lgkmcnt(0)
	v_mfma_f32_32x32x16_bf16 v[16:31], v[4:7], v[108:111], v[16:31]
	ds_read_b128 v[0:3], v205 offset:32768
	ds_read_b128 v[4:7], v205 offset:40960
	s_waitcnt lgkmcnt(1)
	v_mfma_f32_32x32x16_bf16 v[32:47], v[0:3], v[96:99], v[32:47]
	v_or_b32_e32 v0, 0x60, v176
	v_bitop3_b32 v0, v0, v8, v9 bitop3:0xde
	v_add_u32_e32 v202, 0, v0
	s_waitcnt lgkmcnt(0)
	v_mfma_f32_32x32x16_bf16 v[16:31], v[4:7], v[96:99], v[16:31]
	ds_read_b128 v[0:3], v202 offset:32768
	ds_read_b128 v[4:7], v202 offset:40960
	s_waitcnt lgkmcnt(1)
	v_mfma_f32_32x32x16_bf16 v[32:47], v[0:3], v[104:107], v[32:47]
	v_or_b32_e32 v0, 0x80, v176
	v_bitop3_b32 v0, v0, v8, v9 bitop3:0xde
	v_add_u32_e32 v203, 0, v0
	s_waitcnt lgkmcnt(0)
	v_mfma_f32_32x32x16_bf16 v[16:31], v[4:7], v[104:107], v[16:31]
	ds_read_b128 v[0:3], v203 offset:32768
	ds_read_b128 v[4:7], v203 offset:40960
	s_waitcnt lgkmcnt(1)
	v_mfma_f32_32x32x16_bf16 v[32:47], v[0:3], v[116:119], v[32:47]
	v_or_b32_e32 v0, 0xa0, v176
	v_bitop3_b32 v0, v0, v8, v9 bitop3:0xde
	v_add_u32_e32 v206, 0, v0
	ds_read_b128 v[0:3], v206 offset:32768
	s_waitcnt lgkmcnt(1)
	v_mfma_f32_32x32x16_bf16 v[16:31], v[4:7], v[116:119], v[16:31]
	v_and_b32_e32 v4, 0x3fffffc0, v94
	v_lshl_add_u32 v187, v4, 2, s19
	v_and_b32_e32 v4, 0xc0, v185
	v_and_or_b32 v11, v10, 24, v4
	ds_read_b128 v[4:7], v206 offset:40960
	v_and_b32_e32 v10, 0x100, v10
	s_mov_b32 s19, -1
	s_waitcnt lgkmcnt(1)
; #define SLOAD(i, k0) do { sr_[i].vs0 = ld8(&Vh[(long)((k0) + sr) * LDK + sc]); sr_[i].vs1 = ld8(&Vh[(long)((k0) + 32 + sr) * LDK + sc]); \
;     sr_[i].ks0 = ld8(&Kh[(long)((k0) + sr) * LDK + sc]); sr_[i].ks1 = ld8(&Kh[(long)((k0) + 32 + sr) * LDK + sc]); } while (0)
; #define SWRITE(b, i) do { *(bf16x8*)(V_lds + (b) * SHM_V + vst0) = sr_[i].vs0;          \
;     *(bf16x8*)(V_lds + (b) * SHM_V + vst1) = sr_[i].vs1; int kc = sc * 2;               \
;     *(bf16x8*)(K_lds + (b) * SHM_K + KSWZ(sr, kc)) = sr_[i].ks0;                       \
;     *(bf16x8*)(K_lds + (b) * SHM_K + KSWZ(32 + sr, kc)) = sr_[i].ks1; } while (0)
; #define SWAIT() asm volatile("s_waitcnt vmcnt(4)" ::: "memory")
; __device__ __forceinline__ void partialSM(f32x16& p0, f32x16& p1, float& m_reg, float& mn, float& alpha) {
;   constexpr float C = SCALE * 1.4426950408889634f;
;   float pmax = p0[0]; for (int r = 1; r < 16; ++r) pmax = fmaxf(pmax, p0[r]); for (int r = 0; r < 16; ++r) pmax = fmaxf(pmax, p1[r]);
;   { auto rr = __builtin_amdgcn_permlane32_swap(__float_as_uint(pmax), __float_as_uint(pmax), false, false);
;     pmax = fmaxf(__uint_as_float(rr[0]), __uint_as_float(rr[1])); }
;   if (__builtin_expect(__all(pmax - m_reg <= THR / SCALE), 1)) { mn = m_reg; alpha = 1.f; }
;   else { mn = fmaxf(m_reg, pmax); alpha = __builtin_amdgcn_exp2f((m_reg - mn) * C); m_reg = mn; }
;   float mnC = -mn * C;
;   for (int r = 0; r < 16; ++r) p0[r] = fmaf(p0[r], C, mnC); for (int r = 0; r < 16; ++r) p1[r] = fmaf(p1[r], C, mnC);
; __device__ __forceinline__ void attn_body(const bf16_t* Qb, const bf16_t* Kh, const bf16_t* Vh, const bf16_t* Gb, bf16_t* Ob, int seq, char* lds,
;                                           const float* qgain, const float* cosA, const float* sinA, int t0) {
;     ...
;   f32x16 pA0, pA1, pB0, pB1; float mnA, mnB, alA, alB; bf16x8 pa0, pa1, pa2, pa3; const int NT = seq / KVBLK;
;   constexpr int SE = 0, SO = 1;
;   SLOAD(SE, 0); asm volatile("s_waitcnt vmcnt(0)" ::: "memory"); SWRITE(0, SE); __syncthreads();
;   qkt(pA0, pA1, K_lds, qr, r32, hi); partialSM(pA0, pA1, m_reg, mnA, alA);
;   SLOAD(SO, KVBLK); if (2 < NT) SLOAD(SE, 2 * KVBLK);
;   SWAIT(); SWRITE(1, SO); __syncthreads();
	v_mfma_f32_32x32x16_bf16 v[32:47], v[0:3], v[124:127], v[32:47]
	v_lshlrev_b32_e32 v0, 1, v94
	v_and_b32_e32 v12, 32, v0
	v_or_b32_e32 v0, 0xc0, v176
	v_bitop3_b32 v0, v0, v8, v9 bitop3:0xde
	v_add_u32_e32 v207, 0, v0
	ds_read_b128 v[0:3], v207 offset:32768
	v_or3_b32 v74, v11, v12, v10
	s_waitcnt lgkmcnt(1)
	v_mfma_f32_32x32x16_bf16 v[16:31], v[4:7], v[124:127], v[16:31]
	ds_read_b128 v[4:7], v207 offset:40960
	v_add_u32_e32 v191, s21, v74
	v_lshl_add_u32 v188, v181, 2, v187
	s_waitcnt lgkmcnt(1)
	v_mfma_f32_32x32x16_bf16 v[32:47], v[0:3], v[112:115], v[32:47]
	v_or_b32_e32 v0, 0xe0, v176
	v_bitop3_b32 v0, v0, v8, v9 bitop3:0xde
	v_add_u32_e32 v208, 0, v0
	ds_read_b128 v[0:3], v208 offset:32768
	ds_read_b128 v[50:53], v208 offset:40960
	s_waitcnt lgkmcnt(2)
	v_mfma_f32_32x32x16_bf16 v[16:31], v[4:7], v[112:115], v[16:31]
	s_waitcnt lgkmcnt(1)
	v_mfma_f32_32x32x16_bf16 v[32:47], v[0:3], v[120:123], v[32:47]
	v_mov_b64_e32 v[0:1], s[72:73]
	v_mov_b64_e32 v[2:3], s[74:75]
	v_mov_b64_e32 v[4:5], s[76:77]
	v_mov_b64_e32 v[6:7], s[78:79]
	v_mov_b64_e32 v[8:9], s[80:81]
	v_mov_b64_e32 v[10:11], s[82:83]
	v_mov_b64_e32 v[12:13], s[84:85]
	s_waitcnt lgkmcnt(0)
	v_mfma_f32_32x32x16_bf16 v[16:31], v[50:53], v[120:123], v[16:31]
	s_nop 2
	v_max_f32_e32 v50, v33, v33
	v_max_f32_e32 v51, v32, v32
	v_max_f32_e32 v50, v51, v50
	v_max3_f32 v50, v50, v34, v35
	v_max3_f32 v50, v50, v36, v37
	v_max3_f32 v50, v50, v38, v39
	v_max3_f32 v50, v50, v40, v41
	v_max3_f32 v50, v50, v42, v43
	v_max3_f32 v50, v50, v44, v45
	v_max3_f32 v50, v50, v46, v47
	v_max3_f32 v50, v50, v16, v17
	v_max3_f32 v50, v50, v18, v19
	v_max3_f32 v50, v50, v20, v21
	v_max3_f32 v50, v50, v22, v23
	v_max3_f32 v50, v50, v24, v25
	v_max3_f32 v50, v50, v26, v27
	v_max3_f32 v50, v50, v28, v29
	v_max3_f32 v75, v50, v30, v31
	v_add_u32_e32 v50, 64, v48
	v_add_u32_e32 v52, 0x60, v48
	v_mad_i64_i32 v[50:51], s[22:23], v50, s69, 0
	v_mad_i64_i32 v[52:53], s[22:23], v52, s69, 0
	v_or_b32_e32 v50, v50, v180
	v_or_b32_e32 v52, v52, v180
	v_lshlrev_b64 v[58:59], 1, v[50:51]
	v_lshlrev_b64 v[60:61], 1, v[52:53]
	v_lshl_add_u64 v[50:51], s[42:43], 0, v[58:59]
	v_lshl_add_u64 v[54:55], s[42:43], 0, v[60:61]
	v_lshl_add_u64 v[58:59], s[36:37], 0, v[58:59]
	v_lshl_add_u64 v[62:63], s[36:37], 0, v[60:61]
	global_load_dwordx4 v[50:53], v[50:51], off
	s_nop 0
	global_load_dwordx4 v[54:57], v[54:55], off
	s_nop 0
	global_load_dwordx4 v[58:61], v[58:59], off
	s_nop 0
	global_load_dwordx4 v[62:65], v[62:63], off
	s_nop 0
	global_load_dwordx4 v[128:131], v[68:69], off
	global_load_dwordx4 v[132:135], v[72:73], off
	v_lshl_add_u64 v[68:69], s[36:37], 0, v[70:71]
	global_load_dwordx4 v[240:243], v[66:67], off
	global_load_dwordx4 v[246:249], v[68:69], off
	v_add_co_u32_e32 v66, vcc, 0xa0000, v66
	s_nop 1
	v_addc_co_u32_e32 v67, vcc, 0, v67, vcc
	v_add_co_u32_e32 v68, vcc, 0xa0000, v68
	s_nop 1
	v_addc_co_u32_e32 v69, vcc, 0, v69, vcc
	global_load_dwordx4 v[136:139], v[66:67], off
	global_load_dwordx4 v[140:143], v[68:69], off
	v_mov_b32_e32 v76, v75
	s_nop 1
	v_permlane32_swap_b32_e32 v75, v76
	v_max_f32_e32 v66, v76, v76
	v_max_f32_e32 v67, v75, v75
	v_max_f32_e32 v66, v67, v66
	v_add_f32_e32 v67, 0x7149f2ca, v66
	v_max_f32_e32 v66, 0xf149f2ca, v66
	v_cmp_ge_f32_e32 vcc, s71, v67
	v_sub_f32_e32 v67, 0xf149f2ca, v66
	v_mul_f32_e32 v67, 0x3e0293ee, v67
	v_exp_f32_e32 v67, v67
	s_cmp_eq_u64 vcc, exec
	s_cselect_b64 vcc, -1, 0
	v_mov_b32_e32 v68, 0xf149f2ca
	v_cndmask_b32_e32 v164, v66, v68, vcc
	v_mul_f32_e32 v66, 0xbe0293ee, v164
	v_cndmask_b32_e64 v209, v67, 1.0, vcc
	v_mov_b32_e32 v67, v66
	v_fmac_f32_e32 v67, 0x3e0293ee, v47
	v_mov_b64_e32 v[14:15], s[86:87]
	s_movk_i32 s72, 0x2800
	v_pk_fma_f32 v[156:157], v[16:17], s[62:63], v[66:67] op_sel_hi:[1,0,0]
	v_lshl_add_u64 v[16:17], v[48:49], 0, s[38:39]
	v_fmamk_f32 v32, v32, 0x3e0293ee, v66
	v_fmamk_f32 v33, v33, 0x3e0293ee, v66
	v_fmamk_f32 v34, v34, 0x3e0293ee, v66
	v_fmamk_f32 v35, v35, 0x3e0293ee, v66
	v_fmamk_f32 v36, v36, 0x3e0293ee, v66
	v_fmamk_f32 v37, v37, 0x3e0293ee, v66
	v_fmamk_f32 v38, v38, 0x3e0293ee, v66
	v_fmamk_f32 v39, v39, 0x3e0293ee, v66
	v_fmamk_f32 v40, v40, 0x3e0293ee, v66
	v_fmamk_f32 v41, v41, 0x3e0293ee, v66
	v_fmamk_f32 v42, v42, 0x3e0293ee, v66
	v_fmamk_f32 v43, v43, 0x3e0293ee, v66
	v_fmamk_f32 v44, v44, 0x3e0293ee, v66
	v_fmamk_f32 v45, v45, 0x3e0293ee, v66
	v_fmamk_f32 v46, v46, 0x3e0293ee, v66
	v_pk_fma_f32 v[154:155], v[18:19], s[62:63], v[66:67] op_sel_hi:[1,0,0]
	v_mad_u64_u32 v[18:19], s[22:23], v16, s72, 0
	v_and_b32_e32 v16, 15, v94
	v_exp_f32_e32 v175, v32
	v_exp_f32_e32 v216, v33
	v_exp_f32_e32 v161, v34
	v_exp_f32_e32 v213, v35
	v_exp_f32_e32 v162, v36
	v_exp_f32_e32 v174, v37
	v_exp_f32_e32 v163, v38
	v_exp_f32_e32 v173, v39
	v_exp_f32_e32 v170, v40
	v_exp_f32_e32 v172, v41
	v_exp_f32_e32 v169, v42
	v_exp_f32_e32 v171, v43
	v_exp_f32_e32 v166, v44
	v_exp_f32_e32 v168, v45
	v_exp_f32_e32 v165, v46
	v_exp_f32_e32 v167, v67
	v_lshlrev_b32_e32 v16, 4, v16
	s_waitcnt vmcnt(4)
	v_mad_i32_i24 v17, v17, s72, v19
	v_or3_b32 v16, v18, s20, v16
	v_pk_fma_f32 v[150:151], v[30:31], s[62:63], v[66:67] op_sel_hi:[1,0,0]
	v_pk_fma_f32 v[152:153], v[28:29], s[62:63], v[66:67] op_sel_hi:[1,0,0]
	v_pk_fma_f32 v[158:159], v[26:27], s[62:63], v[66:67] op_sel_hi:[1,0,0]
	v_pk_fma_f32 v[144:145], v[24:25], s[62:63], v[66:67] op_sel_hi:[1,0,0]
	v_pk_fma_f32 v[146:147], v[22:23], s[62:63], v[66:67] op_sel_hi:[1,0,0]
	v_pk_fma_f32 v[148:149], v[20:21], s[62:63], v[66:67] op_sel_hi:[1,0,0]
	s_waitcnt vmcnt(7)
	ds_write_b128 v192, v[50:53] offset:16384
	s_waitcnt vmcnt(6)
	ds_write_b128 v193, v[54:57] offset:16384
	s_waitcnt vmcnt(5)
	ds_write_b128 v199, v[58:61] offset:49152
	s_waitcnt vmcnt(4)
	ds_write_b128 v200, v[62:65] offset:49152
	s_addk_i32 s21, 0x4000
	v_lshl_add_u64 v[182:183], s[50:51], 0, v[16:17]
	v_mov_b64_e32 v[62:63], v[14:15]
	v_mov_b64_e32 v[46:47], v[14:15]
	v_mov_b64_e32 v[30:31], v[14:15]
	v_cmp_gt_u32_e64 s[36:37], 32, v186
	v_add_u32_e32 v190, s21, v74
	v_mov_b64_e32 v[60:61], v[12:13]
	v_mov_b64_e32 v[58:59], v[10:11]
	v_mov_b64_e32 v[56:57], v[8:9]
	v_mov_b64_e32 v[54:55], v[6:7]
	v_mov_b64_e32 v[52:53], v[4:5]
	v_mov_b64_e32 v[50:51], v[2:3]
	v_mov_b64_e32 v[48:49], v[0:1]
	v_mov_b64_e32 v[44:45], v[12:13]
	v_mov_b64_e32 v[42:43], v[10:11]
	v_mov_b64_e32 v[40:41], v[8:9]
	v_mov_b64_e32 v[38:39], v[6:7]
	v_mov_b64_e32 v[36:37], v[4:5]
	v_mov_b64_e32 v[34:35], v[2:3]
	v_mov_b64_e32 v[32:33], v[0:1]
	v_mov_b64_e32 v[28:29], v[12:13]
	v_mov_b64_e32 v[26:27], v[10:11]
	v_mov_b64_e32 v[24:25], v[8:9]
	v_mov_b64_e32 v[22:23], v[6:7]
	v_mov_b64_e32 v[20:21], v[4:5]
	v_mov_b64_e32 v[18:19], v[2:3]
	v_mov_b64_e32 v[16:17], v[0:1]
	s_waitcnt lgkmcnt(0)
	s_barrier
	s_waitcnt vmcnt(2)
	ds_write_b128 v199, v[240:243] offset:32768
	ds_write_b128 v200, v[246:249] offset:32768
	v_readfirstlane_b32 s20, v252
	s_cmp_lt_u32 s20, 0x100
	s_cbranch_scc1 .Lpp_entry_skip
	s_barrier
; #define SBAR() __builtin_amdgcn_sched_barrier(0)
; #define SLOAD(i, k0) do { sr_[i].vs0 = ld8(&Vh[(long)((k0) + sr) * LDK + sc]); sr_[i].vs1 = ld8(&Vh[(long)((k0) + 32 + sr) * LDK + sc]); \
;     sr_[i].ks0 = ld8(&Kh[(long)((k0) + sr) * LDK + sc]); sr_[i].ks1 = ld8(&Kh[(long)((k0) + 32 + sr) * LDK + sc]); } while (0)
; __device__ __forceinline__ void finishSM(f32x16& p0, f32x16& p1, float alpha, float& l_reg, bf16x8& pa0, bf16x8& pa1, bf16x8& pa2, bf16x8& pa3) {
;   for (int r = 0; r < 16; ++r) p1[r] = __builtin_amdgcn_exp2f(p1[r]);
;   float ps = 0; for (int r = 0; r < 16; ++r) ps += p0[r]; for (int r = 0; r < 16; ++r) ps += p1[r];
;   { auto rr = __builtin_amdgcn_permlane32_swap(__float_as_uint(ps), __float_as_uint(ps), false, false);
;     ps = __uint_as_float(rr[0]) + __uint_as_float(rr[1]); }
;   l_reg = l_reg * alpha + ps;
;     ...
;   PK4(p0, 0, pa0); PK4(p0, 8, pa1); PK4(p1, 0, pa2); PK4(p1, 8, pa3);
;     ...
; }
; __device__ __forceinline__ void qkt(f32x16& p0, f32x16& p1, const char* Ks, const bf16x8* qr, int r32, int hi) {
;   p0 = f32x16{}; p1 = f32x16{};
;   for (int d0 = 0; d0 < 8; ++d0) { int cb = (d0 * 16 + hi * 8) * 2;
;     bf16x8 b0 = *reinterpret_cast<const bf16x8*>(Ks + KSWZ(r32, cb));
;     bf16x8 b1 = *reinterpret_cast<const bf16x8*>(Ks + KSWZ(32 + r32, cb));
;     p0 = __builtin_amdgcn_mfma_f32_32x32x16_bf16(b0, qr[d0], p0, 0, 0, 0);
;     p1 = __builtin_amdgcn_mfma_f32_32x32x16_bf16(b1, qr[d0], p1, 0, 0, 0); }
; }
; __device__ __forceinline__ void attn_body(const bf16_t* Qb, const bf16_t* Kh, const bf16_t* Vh, const bf16_t* Gb, bf16_t* Ob, int seq, char* lds,
;                                           const float* qgain, const float* cosA, const float* sinA, int t0) {
;     ...
;     SBAR(); qkt(pB0, pB1, K_lds + SHM_K, qr, r32, hi);
;     finishSM(pA0, pA1, alA, l_reg, pa0, pa1, pa2, pa3); SBAR();
;     SLOAD(SO, (j + 2) * KVBLK); SBAR();
;     pv_d0(o, vb0, pa0, pa1, pa2, pa3); partialSM(pB0, pB1, m_reg, mnB, alB);
.Lpp_entry_skip:
.LBB0_259:
	ds_read_b128 v[64:67], v201 offset:49152
	ds_read_b128 v[68:71], v201 offset:57344
	ds_read_b128 v[218:221], v204 offset:49152
	ds_read_b128 v[222:225], v204 offset:57344
	ds_read_b128 v[240:243], v205 offset:49152
	ds_read_b128 v[246:249], v205 offset:57344
	v_add_f32_e32 v160, v216, v175
	s_waitcnt lgkmcnt(5)
	v_mfma_f32_32x32x16_bf16 v[80:95], v[64:67], v[100:103], 0
	v_add_f32_e32 v160, v161, v160
	v_add_f32_e32 v160, v213, v160
	v_add_f32_e32 v160, v162, v160
	v_add_f32_e32 v160, v174, v160
	v_add_f32_e32 v160, v163, v160
	v_add_f32_e32 v160, v173, v160
	v_add_f32_e32 v160, v170, v160
	s_waitcnt lgkmcnt(4)
	v_mfma_f32_32x32x16_bf16 v[64:79], v[68:71], v[100:103], 0
	v_add_f32_e32 v160, v172, v160
	v_add_f32_e32 v160, v169, v160
	v_add_f32_e32 v160, v171, v160
	v_exp_f32_e32 v156, v156
	v_add_f32_e32 v160, v166, v160
	v_exp_f32_e32 v157, v157
	v_add_f32_e32 v160, v168, v160
	s_waitcnt lgkmcnt(3)
	v_mfma_f32_32x32x16_bf16 v[80:95], v[218:221], v[108:111], v[80:95]
	v_exp_f32_e32 v154, v154
	v_add_f32_e32 v160, v165, v160
	v_exp_f32_e32 v155, v155
	v_add_f32_e32 v160, v167, v160
	v_exp_f32_e32 v148, v148
	v_add_f32_e32 v160, v156, v160
	v_exp_f32_e32 v149, v149
	s_waitcnt lgkmcnt(2)
	v_mfma_f32_32x32x16_bf16 v[64:79], v[222:225], v[108:111], v[64:79]
	ds_read_b128 v[218:221], v202 offset:49152
	ds_read_b128 v[222:225], v202 offset:57344
	v_add_f32_e32 v160, v157, v160
	v_exp_f32_e32 v146, v146
	v_add_f32_e32 v160, v154, v160
	v_exp_f32_e32 v147, v147
	v_add_f32_e32 v160, v155, v160
	v_exp_f32_e32 v144, v144
	s_waitcnt lgkmcnt(3)
	v_mfma_f32_32x32x16_bf16 v[80:95], v[240:243], v[96:99], v[80:95]
	v_add_f32_e32 v160, v148, v160
	v_exp_f32_e32 v145, v145
	v_add_f32_e32 v160, v149, v160
	v_exp_f32_e32 v158, v158
	v_add_f32_e32 v160, v146, v160
	v_exp_f32_e32 v159, v159
	v_add_f32_e32 v160, v147, v160
	s_waitcnt lgkmcnt(2)
	v_mfma_f32_32x32x16_bf16 v[64:79], v[246:249], v[96:99], v[64:79]
	ds_read_b128 v[240:243], v203 offset:49152
	ds_read_b128 v[246:249], v203 offset:57344
	v_exp_f32_e32 v152, v152
	v_add_f32_e32 v160, v144, v160
	v_exp_f32_e32 v153, v153
	v_add_f32_e32 v160, v145, v160
	v_exp_f32_e32 v150, v150
	v_add_f32_e32 v160, v158, v160
	s_waitcnt lgkmcnt(3)
	v_mfma_f32_32x32x16_bf16 v[80:95], v[218:221], v[104:107], v[80:95]
	v_exp_f32_e32 v151, v151
	v_add_f32_e32 v160, v159, v160
	v_add_f32_e32 v160, v152, v160
	v_add_f32_e32 v160, v153, v160
	v_add_f32_e32 v160, v150, v160
	v_add_f32_e32 v210, v151, v160
	v_mov_b32_e32 v211, v210
	s_waitcnt lgkmcnt(2)
	v_mfma_f32_32x32x16_bf16 v[64:79], v[222:225], v[104:107], v[64:79]
	ds_read_b128 v[218:221], v206 offset:49152
	ds_read_b128 v[222:225], v206 offset:57344
	v_permlane32_swap_b32_e32 v210, v211
	s_waitcnt lgkmcnt(3)
	v_mfma_f32_32x32x16_bf16 v[80:95], v[240:243], v[116:119], v[80:95]
	s_waitcnt lgkmcnt(2)
	v_mfma_f32_32x32x16_bf16 v[64:79], v[246:249], v[116:119], v[64:79]
	ds_read_b128 v[240:243], v207 offset:49152
	ds_read_b128 v[246:249], v207 offset:57344
	s_waitcnt lgkmcnt(3)
	v_mfma_f32_32x32x16_bf16 v[80:95], v[218:221], v[124:127], v[80:95]
	s_waitcnt lgkmcnt(2)
	v_mfma_f32_32x32x16_bf16 v[64:79], v[222:225], v[124:127], v[64:79]
	ds_read_b128 v[218:221], v208 offset:49152
	ds_read_b128 v[222:225], v208 offset:57344
	s_waitcnt lgkmcnt(3)
	v_mfma_f32_32x32x16_bf16 v[80:95], v[240:243], v[112:115], v[80:95]
	s_waitcnt lgkmcnt(2)
	v_mfma_f32_32x32x16_bf16 v[64:79], v[246:249], v[112:115], v[64:79]
	v_cvt_pk_bf16_f32 v160, v175, v216
	v_cvt_pk_bf16_f32 v161, v161, v213
	v_cvt_pk_bf16_f32 v162, v162, v174
	v_cvt_pk_bf16_f32 v163, v163, v173
	v_cvt_pk_bf16_f32 v170, v170, v172
	v_cvt_pk_bf16_f32 v171, v169, v171
	s_waitcnt lgkmcnt(1)
	v_mfma_f32_32x32x16_bf16 v[80:95], v[218:221], v[120:123], v[80:95]
	v_cvt_pk_bf16_f32 v172, v166, v168
	v_cvt_pk_bf16_f32 v173, v165, v167
	v_cvt_pk_bf16_f32 v166, v156, v157
	v_cvt_pk_bf16_f32 v167, v154, v155
	v_cvt_pk_bf16_f32 v168, v148, v149
	v_cvt_pk_bf16_f32 v169, v146, v147
	v_cvt_pk_bf16_f32 v212, v144, v145
	s_waitcnt lgkmcnt(0)
	v_mfma_f32_32x32x16_bf16 v[64:79], v[222:225], v[120:123], v[64:79]
	v_cvt_pk_bf16_f32 v213, v158, v159
	v_cvt_pk_bf16_f32 v214, v152, v153
	v_permlane32_swap_b32_e32 v160, v162
	v_cvt_pk_bf16_f32 v215, v150, v151
	v_permlane32_swap_b32_e32 v212, v214
	v_permlane32_swap_b32_e32 v161, v163
	v_permlane32_swap_b32_e32 v170, v172
	v_permlane32_swap_b32_e32 v171, v173
	v_permlane32_swap_b32_e32 v166, v168
	v_permlane32_swap_b32_e32 v167, v169
	v_permlane32_swap_b32_e32 v213, v215
	s_mov_b32 s20, 0xfff10000
	s_mov_b32 s21, -1
	v_lshl_add_u64 v[148:149], v[182:183], 0, s[20:21]
	s_mov_b32 s20, 0xfff60000
	v_lshl_add_u64 v[152:153], v[182:183], 0, s[20:21]
	s_mov_b32 s20, 0xfffb0000
	v_lshl_add_u64 v[250:251], v[182:183], 0, s[20:21]
	global_load_dwordx4 v[144:147], v[148:149], off
	global_load_dwordx4 v[148:151], v[250:251], off offset:-1024
	global_load_dwordx4 v[156:159], v[152:153], off
	global_load_dwordx4 v[152:155], v[182:183], off offset:-1024
	ds_read_b64_tr_b16 v[216:217], v191 offset:0
	ds_read_b64_tr_b16 v[218:219], v191 offset:0x800
	ds_read_b64_tr_b16 v[220:221], v191 offset:0x1000
	ds_read_b64_tr_b16 v[222:223], v191 offset:0x1800
	ds_read_b64_tr_b16 v[224:225], v191 offset:0x2000
	ds_read_b64_tr_b16 v[226:227], v191 offset:0x2800
	ds_read_b64_tr_b16 v[228:229], v191 offset:0x3000
	ds_read_b64_tr_b16 v[230:231], v191 offset:0x3800
	s_waitcnt lgkmcnt(0)
; #define SBAR() __builtin_amdgcn_sched_barrier(0)
; __device__ __forceinline__ void partialSM(f32x16& p0, f32x16& p1, float& m_reg, float& mn, float& alpha) {
;   constexpr float C = SCALE * 1.4426950408889634f;
;   float pmax = p0[0]; for (int r = 1; r < 16; ++r) pmax = fmaxf(pmax, p0[r]); for (int r = 0; r < 16; ++r) pmax = fmaxf(pmax, p1[r]);
;   { auto rr = __builtin_amdgcn_permlane32_swap(__float_as_uint(pmax), __float_as_uint(pmax), false, false);
;     pmax = fmaxf(__uint_as_float(rr[0]), __uint_as_float(rr[1])); }
;   if (__builtin_expect(__all(pmax - m_reg <= THR / SCALE), 1)) { mn = m_reg; alpha = 1.f; }
;   else { mn = fmaxf(m_reg, pmax); alpha = __builtin_amdgcn_exp2f((m_reg - mn) * C); m_reg = mn; }
; template <int D0> __device__ __forceinline__ void pv_one(f32x16& od, int vb, bf16x8 pa0, bf16x8 pa1, bf16x8 pa2, bf16x8 pa3) {
;   const s16x4 l0 = tr_read<v_rd_off(D0, 0, 0)>(vb), h0 = tr_read<v_rd_off(D0, 0, 1)>(vb), l1 = tr_read<v_rd_off(D0, 1, 0)>(vb), h1 = tr_read<v_rd_off(D0, 1, 1)>(vb);
;   const s16x4 l2 = tr_read<v_rd_off(D0, 2, 0)>(vb), h2 = tr_read<v_rd_off(D0, 2, 1)>(vb), l3 = tr_read<v_rd_off(D0, 3, 0)>(vb), h3 = tr_read<v_rd_off(D0, 3, 1)>(vb);
;   asm volatile("s_waitcnt lgkmcnt(0)" ::: "memory"); SBAR();
;     ...
;   od = __builtin_amdgcn_mfma_f32_32x32x16_bf16(pa0, PK(l0, h0), od, 0, 0, 0);
;   od = __builtin_amdgcn_mfma_f32_32x32x16_bf16(pa1, PK(l1, h1), od, 0, 0, 0);
;   od = __builtin_amdgcn_mfma_f32_32x32x16_bf16(pa2, PK(l2, h2), od, 0, 0, 0);
;   od = __builtin_amdgcn_mfma_f32_32x32x16_bf16(pa3, PK(l3, h3), od, 0, 0, 0);
;     ...
; }
; __device__ __forceinline__ void pv_d0(f32x16* o, int vb, bf16x8 pa0, bf16x8 pa1, bf16x8 pa2, bf16x8 pa3) {
;   pv_one<0>(o[0], vb, pa0, pa1, pa2, pa3); pv_one<1>(o[1], vb, pa0, pa1, pa2, pa3); pv_one<2>(o[2], vb, pa0, pa1, pa2, pa3); pv_one<3>(o[3], vb, pa0, pa1, pa2, pa3);
; }
	s_nop 0
	v_mfma_f32_32x32x16_bf16 v[0:15], v[160:163], v[216:219], v[0:15]
	ds_read_b64_tr_b16 v[216:217], v191 offset:0x200
	ds_read_b64_tr_b16 v[218:219], v191 offset:0xa00
	v_mfma_f32_32x32x16_bf16 v[0:15], v[170:173], v[220:223], v[0:15]
	ds_read_b64_tr_b16 v[220:221], v191 offset:0x1200
	ds_read_b64_tr_b16 v[222:223], v191 offset:0x1a00
	v_mfma_f32_32x32x16_bf16 v[0:15], v[166:169], v[224:227], v[0:15]
	ds_read_b64_tr_b16 v[224:225], v191 offset:0x2200
	ds_read_b64_tr_b16 v[226:227], v191 offset:0x2a00
	v_mfma_f32_32x32x16_bf16 v[0:15], v[212:215], v[228:231], v[0:15]
	ds_read_b64_tr_b16 v[228:229], v191 offset:0x3200
	ds_read_b64_tr_b16 v[230:231], v191 offset:0x3a00
	s_waitcnt lgkmcnt(0)
	v_mfma_f32_32x32x16_bf16 v[48:63], v[160:163], v[216:219], v[48:63]
	ds_read_b64_tr_b16 v[216:217], v191 offset:0x400
	ds_read_b64_tr_b16 v[218:219], v191 offset:0xc00
	v_mfma_f32_32x32x16_bf16 v[48:63], v[170:173], v[220:223], v[48:63]
	ds_read_b64_tr_b16 v[220:221], v191 offset:0x1400
	ds_read_b64_tr_b16 v[222:223], v191 offset:0x1c00
	v_mfma_f32_32x32x16_bf16 v[48:63], v[166:169], v[224:227], v[48:63]
	ds_read_b64_tr_b16 v[224:225], v191 offset:0x2400
	ds_read_b64_tr_b16 v[226:227], v191 offset:0x2c00
	v_mfma_f32_32x32x16_bf16 v[48:63], v[212:215], v[228:231], v[48:63]
	ds_read_b64_tr_b16 v[228:229], v191 offset:0x3400
	ds_read_b64_tr_b16 v[230:231], v191 offset:0x3c00
	s_waitcnt lgkmcnt(0)
	v_mfma_f32_32x32x16_bf16 v[32:47], v[160:163], v[216:219], v[32:47]
	ds_read_b64_tr_b16 v[216:217], v191 offset:0x600
	ds_read_b64_tr_b16 v[218:219], v191 offset:0xe00
	v_mfma_f32_32x32x16_bf16 v[32:47], v[170:173], v[220:223], v[32:47]
	ds_read_b64_tr_b16 v[220:221], v191 offset:0x1600
	ds_read_b64_tr_b16 v[222:223], v191 offset:0x1e00
	v_mfma_f32_32x32x16_bf16 v[32:47], v[166:169], v[224:227], v[32:47]
	ds_read_b64_tr_b16 v[224:225], v191 offset:0x2600
	ds_read_b64_tr_b16 v[226:227], v191 offset:0x2e00
	v_mfma_f32_32x32x16_bf16 v[32:47], v[212:215], v[228:231], v[32:47]
	ds_read_b64_tr_b16 v[228:229], v191 offset:0x3600
	ds_read_b64_tr_b16 v[230:231], v191 offset:0x3e00
	s_waitcnt lgkmcnt(0)
	v_mfma_f32_32x32x16_bf16 v[16:31], v[160:163], v[216:219], v[16:31]
	v_max_f32_e32 v160, v80, v81
	v_max3_f32 v160, v160, v82, v83
	v_max3_f32 v160, v160, v84, v85
	v_max3_f32 v160, v160, v86, v87
	v_max3_f32 v160, v160, v88, v89
	v_max3_f32 v160, v160, v90, v91
	v_max3_f32 v160, v160, v92, v93
	v_mfma_f32_32x32x16_bf16 v[16:31], v[170:173], v[220:223], v[16:31]
	v_max3_f32 v160, v160, v94, v95
	v_max3_f32 v160, v160, v64, v65
	v_max3_f32 v160, v160, v66, v67
	v_max3_f32 v160, v160, v68, v69
	v_max3_f32 v160, v160, v70, v71
	v_max3_f32 v160, v160, v72, v73
	v_max3_f32 v160, v160, v74, v75
	v_max3_f32 v160, v160, v76, v77
	v_mfma_f32_32x32x16_bf16 v[16:31], v[166:169], v[224:227], v[16:31]
	v_max3_f32 v160, v160, v78, v79
	v_mov_b32_e32 v161, v160
	s_nop 1
	v_permlane32_swap_b32_e32 v160, v161
	v_max_f32_e32 v160, v160, v161
	v_sub_f32_e32 v161, v160, v164
	v_cmp_ge_f32_e32 vcc, s71, v161
	v_max_f32_e32 v160, v164, v160
	v_mfma_f32_32x32x16_bf16 v[16:31], v[212:215], v[228:231], v[16:31]
	v_sub_f32_e32 v161, v164, v160
	v_mul_f32_e32 v161, 0x3e0293ee, v161
	v_exp_f32_e32 v161, v161
	s_cmp_eq_u64 vcc, exec
	s_cselect_b64 s[38:39], -1, 0
	s_barrier
	s_waitcnt vmcnt(4)
	v_cndmask_b32_e64 v212, v161, 1.0, s[38:39]
	v_cmp_gt_f32_e32 vcc, 1.0, v212
	s_cbranch_vccz .LBB0_263
	s_and_saveexec_b64 s[42:43], s[36:37]
	ds_write_b32 v188, v212 offset:128
	s_or_b64 exec, exec, s[42:43]
	s_waitcnt lgkmcnt(0)
	v_add_u32_e32 v161, v187, v176
	ds_read_b128 v[166:169], v161 offset:224
	ds_read_b128 v[170:173], v161 offset:192
	ds_read_b128 v[214:217], v161 offset:160
	ds_read_b128 v[218:221], v161 offset:128
	s_waitcnt lgkmcnt(3)
	v_pk_mul_f32 v[12:13], v[12:13], v[166:167]
	s_waitcnt lgkmcnt(2)
	v_pk_mul_f32 v[8:9], v[8:9], v[170:171]
	s_waitcnt lgkmcnt(1)
	v_pk_mul_f32 v[4:5], v[4:5], v[214:215]
	v_pk_mul_f32 v[14:15], v[14:15], v[168:169]
	v_pk_mul_f32 v[10:11], v[10:11], v[172:173]
	v_pk_mul_f32 v[6:7], v[6:7], v[216:217]
	s_waitcnt lgkmcnt(0)
	v_pk_mul_f32 v[2:3], v[2:3], v[220:221]
	v_pk_mul_f32 v[0:1], v[0:1], v[218:219]
	v_pk_mul_f32 v[60:61], v[60:61], v[166:167]
	v_pk_mul_f32 v[56:57], v[56:57], v[170:171]
	v_pk_mul_f32 v[52:53], v[52:53], v[214:215]
	v_pk_mul_f32 v[62:63], v[62:63], v[168:169]
	v_pk_mul_f32 v[58:59], v[58:59], v[172:173]
	v_pk_mul_f32 v[54:55], v[54:55], v[216:217]
	v_pk_mul_f32 v[50:51], v[50:51], v[220:221]
	v_pk_mul_f32 v[48:49], v[48:49], v[218:219]
	v_pk_mul_f32 v[44:45], v[44:45], v[166:167]
	v_pk_mul_f32 v[40:41], v[40:41], v[170:171]
	v_pk_mul_f32 v[36:37], v[36:37], v[214:215]
	v_pk_mul_f32 v[46:47], v[46:47], v[168:169]
	v_pk_mul_f32 v[42:43], v[42:43], v[172:173]
	v_pk_mul_f32 v[38:39], v[38:39], v[216:217]
	v_pk_mul_f32 v[34:35], v[34:35], v[220:221]
	v_pk_mul_f32 v[32:33], v[32:33], v[218:219]
	v_pk_mul_f32 v[28:29], v[28:29], v[166:167]
	v_pk_mul_f32 v[24:25], v[24:25], v[170:171]
	v_pk_mul_f32 v[20:21], v[20:21], v[214:215]
	v_pk_mul_f32 v[30:31], v[30:31], v[168:169]
	v_pk_mul_f32 v[26:27], v[26:27], v[172:173]
	v_pk_mul_f32 v[22:23], v[22:23], v[216:217]
	v_pk_mul_f32 v[18:19], v[18:19], v[220:221]
	v_pk_mul_f32 v[16:17], v[16:17], v[218:219]
; __device__ __forceinline__ void partialSM(f32x16& p0, f32x16& p1, float& m_reg, float& mn, float& alpha) {
;   constexpr float C = SCALE * 1.4426950408889634f;
;   float pmax = p0[0]; for (int r = 1; r < 16; ++r) pmax = fmaxf(pmax, p0[r]); for (int r = 0; r < 16; ++r) pmax = fmaxf(pmax, p1[r]);
;   { auto rr = __builtin_amdgcn_permlane32_swap(__float_as_uint(pmax), __float_as_uint(pmax), false, false);
;     pmax = fmaxf(__uint_as_float(rr[0]), __uint_as_float(rr[1])); }
;   if (__builtin_expect(__all(pmax - m_reg <= THR / SCALE), 1)) { mn = m_reg; alpha = 1.f; }
;   else { mn = fmaxf(m_reg, pmax); alpha = __builtin_amdgcn_exp2f((m_reg - mn) * C); m_reg = mn; }
;   float mnC = -mn * C;
;   for (int r = 0; r < 16; ++r) p0[r] = fmaf(p0[r], C, mnC); for (int r = 0; r < 16; ++r) p1[r] = fmaf(p1[r], C, mnC);
;   for (int r = 0; r < 16; ++r) p0[r] = __builtin_amdgcn_exp2f(p0[r]);
; }
; __device__ __forceinline__ void finishSM(f32x16& p0, f32x16& p1, float alpha, float& l_reg, bf16x8& pa0, bf16x8& pa1, bf16x8& pa2, bf16x8& pa3) {
;   for (int r = 0; r < 16; ++r) p1[r] = __builtin_amdgcn_exp2f(p1[r]);
;   float ps = 0; for (int r = 0; r < 16; ++r) ps += p0[r]; for (int r = 0; r < 16; ++r) ps += p1[r];
;   { auto rr = __builtin_amdgcn_permlane32_swap(__float_as_uint(ps), __float_as_uint(ps), false, false);
;     ps = __uint_as_float(rr[0]) + __uint_as_float(rr[1]); }
;   l_reg = l_reg * alpha + ps;
;     ...
;   PK4(p0, 0, pa0); PK4(p0, 8, pa1); PK4(p1, 0, pa2); PK4(p1, 8, pa3);
;     ...
; }
; __device__ __forceinline__ void qkt(f32x16& p0, f32x16& p1, const char* Ks, const bf16x8* qr, int r32, int hi) {
;   p0 = f32x16{}; p1 = f32x16{};
;   for (int d0 = 0; d0 < 8; ++d0) { int cb = (d0 * 16 + hi * 8) * 2;
;     bf16x8 b0 = *reinterpret_cast<const bf16x8*>(Ks + KSWZ(r32, cb));
;     bf16x8 b1 = *reinterpret_cast<const bf16x8*>(Ks + KSWZ(32 + r32, cb));
;     p0 = __builtin_amdgcn_mfma_f32_32x32x16_bf16(b0, qr[d0], p0, 0, 0, 0);
;     p1 = __builtin_amdgcn_mfma_f32_32x32x16_bf16(b1, qr[d0], p1, 0, 0, 0); }
; }
; __device__ __forceinline__ void attn_body(const bf16_t* Qb, const bf16_t* Kh, const bf16_t* Vh, const bf16_t* Gb, bf16_t* Ob, int seq, char* lds,
;                                           const float* qgain, const float* cosA, const float* sinA, int t0) {
;     ...
;     __syncthreads(); SWAIT(); SWRITE(0, SE);
;     RESC(alB); __syncthreads();
.LBB0_263:
	v_cndmask_b32_e64 v213, v160, v164, s[38:39]
	v_mul_f32_e32 v214, 0xbe0293ee, v213
	v_fmamk_f32 v80, v80, 0x3e0293ee, v214
	v_fmamk_f32 v81, v81, 0x3e0293ee, v214
	v_fmamk_f32 v82, v82, 0x3e0293ee, v214
	v_fmamk_f32 v83, v83, 0x3e0293ee, v214
	v_fmamk_f32 v84, v84, 0x3e0293ee, v214
	v_fmamk_f32 v85, v85, 0x3e0293ee, v214
	v_fmamk_f32 v86, v86, 0x3e0293ee, v214
	v_fmamk_f32 v87, v87, 0x3e0293ee, v214
	v_fmamk_f32 v88, v88, 0x3e0293ee, v214
	v_fmamk_f32 v89, v89, 0x3e0293ee, v214
	v_fmamk_f32 v90, v90, 0x3e0293ee, v214
	v_fmamk_f32 v91, v91, 0x3e0293ee, v214
	v_fmamk_f32 v92, v92, 0x3e0293ee, v214
	v_fmamk_f32 v93, v93, 0x3e0293ee, v214
	v_fmamk_f32 v94, v94, 0x3e0293ee, v214
	v_fmamk_f32 v95, v95, 0x3e0293ee, v214
	v_exp_f32_e32 v160, v80
	v_exp_f32_e32 v175, v81
	v_exp_f32_e32 v161, v82
	v_exp_f32_e32 v174, v83
	v_exp_f32_e32 v162, v84
	v_exp_f32_e32 v173, v85
	v_exp_f32_e32 v163, v86
	v_exp_f32_e32 v172, v87
	v_exp_f32_e32 v164, v88
	v_exp_f32_e32 v171, v89
	v_exp_f32_e32 v165, v90
	v_exp_f32_e32 v170, v91
	v_exp_f32_e32 v166, v92
	v_exp_f32_e32 v169, v93
	v_exp_f32_e32 v167, v94
	v_exp_f32_e32 v168, v95
	v_fmamk_f32 v223, v64, 0x3e0293ee, v214
	v_fmamk_f32 v224, v65, 0x3e0293ee, v214
	v_fmamk_f32 v225, v66, 0x3e0293ee, v214
	v_fmamk_f32 v226, v67, 0x3e0293ee, v214
	v_fmamk_f32 v227, v68, 0x3e0293ee, v214
	v_fmamk_f32 v216, v69, 0x3e0293ee, v214
	v_fmamk_f32 v217, v70, 0x3e0293ee, v214
	v_fmamk_f32 v218, v71, 0x3e0293ee, v214
	v_fmamk_f32 v219, v72, 0x3e0293ee, v214
	v_fmamk_f32 v220, v73, 0x3e0293ee, v214
	v_fmamk_f32 v221, v74, 0x3e0293ee, v214
	v_fmamk_f32 v222, v75, 0x3e0293ee, v214
	v_fmamk_f32 v215, v76, 0x3e0293ee, v214
	v_fmamk_f32 v228, v77, 0x3e0293ee, v214
	v_fmamk_f32 v229, v78, 0x3e0293ee, v214
	v_fmac_f32_e32 v214, 0x3e0293ee, v79
	s_add_i32 s19, s19, 2
	s_waitcnt lgkmcnt(0)
	s_barrier
	ds_write_b128 v192, v[128:131]
	ds_write_b128 v193, v[132:135]
	ds_write_b128 v199, v[136:139] offset:49152
	ds_write_b128 v200, v[140:143] offset:49152
	ds_read_b128 v[64:67], v201 offset:32768
	ds_read_b128 v[68:71], v201 offset:40960
	ds_read_b128 v[230:233], v204 offset:32768
	ds_read_b128 v[234:237], v204 offset:40960
	ds_read_b128 v[240:243], v205 offset:32768
	ds_read_b128 v[246:249], v205 offset:40960
	v_exp_f32_e32 v194, v223
	v_exp_f32_e32 v223, v227
	s_waitcnt lgkmcnt(5)
	v_mfma_f32_32x32x16_bf16 v[80:95], v[64:67], v[100:103], 0
	v_exp_f32_e32 v227, v214
	v_add_f32_e32 v214, v175, v160
	v_add_f32_e32 v214, v161, v214
	v_add_f32_e32 v214, v174, v214
	v_add_f32_e32 v214, v162, v214
	v_add_f32_e32 v214, v173, v214
	s_waitcnt lgkmcnt(4)
	v_mfma_f32_32x32x16_bf16 v[64:79], v[68:71], v[100:103], 0
	v_add_f32_e32 v214, v163, v214
	v_add_f32_e32 v214, v172, v214
	v_add_f32_e32 v214, v164, v214
	v_add_f32_e32 v214, v171, v214
	v_add_f32_e32 v214, v165, v214
	v_add_f32_e32 v214, v170, v214
	v_add_f32_e32 v214, v166, v214
	s_waitcnt lgkmcnt(3)
	v_mfma_f32_32x32x16_bf16 v[80:95], v[230:233], v[108:111], v[80:95]
	v_exp_f32_e32 v195, v224
	v_add_f32_e32 v214, v169, v214
	v_exp_f32_e32 v196, v225
	v_add_f32_e32 v214, v167, v214
	v_exp_f32_e32 v197, v226
	v_add_f32_e32 v214, v168, v214
	v_add_f32_e32 v214, v194, v214
	s_waitcnt lgkmcnt(2)
	v_mfma_f32_32x32x16_bf16 v[64:79], v[234:237], v[108:111], v[64:79]
	ds_read_b128 v[230:233], v202 offset:32768
	ds_read_b128 v[234:237], v202 offset:40960
	v_exp_f32_e32 v216, v216
	v_add_f32_e32 v214, v195, v214
	v_exp_f32_e32 v217, v217
	v_add_f32_e32 v214, v196, v214
	v_exp_f32_e32 v218, v218
	v_add_f32_e32 v214, v197, v214
	s_waitcnt lgkmcnt(3)
	v_mfma_f32_32x32x16_bf16 v[80:95], v[240:243], v[96:99], v[80:95]
	v_exp_f32_e32 v219, v219
	v_add_f32_e32 v214, v223, v214
	v_exp_f32_e32 v220, v220
	v_add_f32_e32 v214, v216, v214
	v_exp_f32_e32 v221, v221
	v_add_f32_e32 v214, v217, v214
	v_exp_f32_e32 v222, v222
	s_waitcnt lgkmcnt(2)
	v_mfma_f32_32x32x16_bf16 v[64:79], v[246:249], v[96:99], v[64:79]
	ds_read_b128 v[240:243], v203 offset:32768
	ds_read_b128 v[246:249], v203 offset:40960
	v_add_f32_e32 v214, v218, v214
	v_exp_f32_e32 v224, v215
	v_add_f32_e32 v214, v219, v214
	v_exp_f32_e32 v225, v228
	v_add_f32_e32 v214, v220, v214
	v_exp_f32_e32 v226, v229
	s_waitcnt lgkmcnt(3)
	v_mfma_f32_32x32x16_bf16 v[80:95], v[230:233], v[104:107], v[80:95]
	v_add_f32_e32 v214, v221, v214
	v_add_f32_e32 v214, v222, v214
	v_add_f32_e32 v214, v224, v214
	v_add_f32_e32 v214, v225, v214
	v_add_f32_e32 v214, v226, v214
	v_add_f32_e32 v214, v227, v214
	v_mov_b32_e32 v215, v214
	s_waitcnt lgkmcnt(2)
	v_mfma_f32_32x32x16_bf16 v[64:79], v[234:237], v[104:107], v[64:79]
	ds_read_b128 v[230:233], v206 offset:32768
	ds_read_b128 v[234:237], v206 offset:40960
	v_permlane32_swap_b32_e32 v214, v215
	s_waitcnt lgkmcnt(3)
	v_mfma_f32_32x32x16_bf16 v[80:95], v[240:243], v[116:119], v[80:95]
	s_waitcnt lgkmcnt(2)
	v_mfma_f32_32x32x16_bf16 v[64:79], v[246:249], v[116:119], v[64:79]
	ds_read_b128 v[240:243], v207 offset:32768
	ds_read_b128 v[246:249], v207 offset:40960
	s_waitcnt lgkmcnt(3)
	v_mfma_f32_32x32x16_bf16 v[80:95], v[230:233], v[124:127], v[80:95]
	s_waitcnt lgkmcnt(2)
	v_mfma_f32_32x32x16_bf16 v[64:79], v[234:237], v[124:127], v[64:79]
	ds_read_b128 v[230:233], v208 offset:32768
	ds_read_b128 v[234:237], v208 offset:40960
	s_waitcnt lgkmcnt(3)
	v_mfma_f32_32x32x16_bf16 v[80:95], v[240:243], v[112:115], v[80:95]
	s_waitcnt lgkmcnt(2)
	v_mfma_f32_32x32x16_bf16 v[64:79], v[246:249], v[112:115], v[64:79]
	v_cvt_pk_bf16_f32 v160, v160, v175
	v_cvt_pk_bf16_f32 v161, v161, v174
	v_cvt_pk_bf16_f32 v162, v162, v173
	v_cvt_pk_bf16_f32 v163, v163, v172
	v_cvt_pk_bf16_f32 v164, v164, v171
	v_cvt_pk_bf16_f32 v165, v165, v170
	s_waitcnt lgkmcnt(1)
	v_mfma_f32_32x32x16_bf16 v[80:95], v[230:233], v[120:123], v[80:95]
	v_cvt_pk_bf16_f32 v166, v166, v169
	v_cvt_pk_bf16_f32 v167, v167, v168
	v_cvt_pk_bf16_f32 v168, v194, v195
	v_cvt_pk_bf16_f32 v169, v196, v197
	v_cvt_pk_bf16_f32 v170, v223, v216
	v_cvt_pk_bf16_f32 v171, v217, v218
	v_cvt_pk_bf16_f32 v172, v219, v220
	s_waitcnt lgkmcnt(0)
	v_mfma_f32_32x32x16_bf16 v[64:79], v[234:237], v[120:123], v[64:79]
	v_cvt_pk_bf16_f32 v173, v221, v222
	v_cvt_pk_bf16_f32 v174, v224, v225
	v_cvt_pk_bf16_f32 v175, v226, v227
	v_permlane32_swap_b32_e32 v160, v162
	v_permlane32_swap_b32_e32 v161, v163
	v_permlane32_swap_b32_e32 v164, v166
	v_permlane32_swap_b32_e32 v165, v167
	v_permlane32_swap_b32_e32 v168, v170
	v_permlane32_swap_b32_e32 v169, v171
	v_permlane32_swap_b32_e32 v172, v174
	v_permlane32_swap_b32_e32 v173, v175
	s_cmp_gt_u32 s19, 60
	s_cselect_b64 s[42:43], -1, 0
	s_and_b64 vcc, exec, s[42:43]
	s_cbranch_vccnz .LBB0_265
; #define SBAR() __builtin_amdgcn_sched_barrier(0)
; #define SLOAD(i, k0) do { sr_[i].vs0 = ld8(&Vh[(long)((k0) + sr) * LDK + sc]); sr_[i].vs1 = ld8(&Vh[(long)((k0) + 32 + sr) * LDK + sc]); \
;     sr_[i].ks0 = ld8(&Kh[(long)((k0) + sr) * LDK + sc]); sr_[i].ks1 = ld8(&Kh[(long)((k0) + 32 + sr) * LDK + sc]); } while (0)
; #define SWRITE(b, i) do { *(bf16x8*)(V_lds + (b) * SHM_V + vst0) = sr_[i].vs0;          \
;     *(bf16x8*)(V_lds + (b) * SHM_V + vst1) = sr_[i].vs1; int kc = sc * 2;               \
;     *(bf16x8*)(K_lds + (b) * SHM_K + KSWZ(sr, kc)) = sr_[i].ks0;                       \
;     *(bf16x8*)(K_lds + (b) * SHM_K + KSWZ(32 + sr, kc)) = sr_[i].ks1; } while (0)
; #define SWAIT() asm volatile("s_waitcnt vmcnt(4)" ::: "memory")
; template <int D0> __device__ __forceinline__ void pv_one(f32x16& od, int vb, bf16x8 pa0, bf16x8 pa1, bf16x8 pa2, bf16x8 pa3) {
;   const s16x4 l0 = tr_read<v_rd_off(D0, 0, 0)>(vb), h0 = tr_read<v_rd_off(D0, 0, 1)>(vb), l1 = tr_read<v_rd_off(D0, 1, 0)>(vb), h1 = tr_read<v_rd_off(D0, 1, 1)>(vb);
;   const s16x4 l2 = tr_read<v_rd_off(D0, 2, 0)>(vb), h2 = tr_read<v_rd_off(D0, 2, 1)>(vb), l3 = tr_read<v_rd_off(D0, 3, 0)>(vb), h3 = tr_read<v_rd_off(D0, 3, 1)>(vb);
;   asm volatile("s_waitcnt lgkmcnt(0)" ::: "memory"); SBAR();
;     ...
;   od = __builtin_amdgcn_mfma_f32_32x32x16_bf16(pa0, PK(l0, h0), od, 0, 0, 0);
;   od = __builtin_amdgcn_mfma_f32_32x32x16_bf16(pa1, PK(l1, h1), od, 0, 0, 0);
;   od = __builtin_amdgcn_mfma_f32_32x32x16_bf16(pa2, PK(l2, h2), od, 0, 0, 0);
;   od = __builtin_amdgcn_mfma_f32_32x32x16_bf16(pa3, PK(l3, h3), od, 0, 0, 0);
;     ...
; }
; __device__ __forceinline__ void pv_d0(f32x16* o, int vb, bf16x8 pa0, bf16x8 pa1, bf16x8 pa2, bf16x8 pa3) {
;   pv_one<0>(o[0], vb, pa0, pa1, pa2, pa3); pv_one<1>(o[1], vb, pa0, pa1, pa2, pa3); pv_one<2>(o[2], vb, pa0, pa1, pa2, pa3); pv_one<3>(o[3], vb, pa0, pa1, pa2, pa3);
; }
; __device__ __forceinline__ void attn_body(const bf16_t* Qb, const bf16_t* Kh, const bf16_t* Vh, const bf16_t* Gb, bf16_t* Ob, int seq, char* lds,
;                                           const float* qgain, const float* cosA, const float* sinA, int t0) {
;     ...
;     if (j + 3 < NT) SLOAD(SE, (j + 3) * KVBLK); SBAR();
;     pv_d0(o, vb0 + (int)SHM_V, pa0, pa1, pa2, pa3); partialSM(pA0, pA1, m_reg, mnA, alA);
;     __syncthreads(); SWAIT(); SWRITE(1, SO);
	s_mov_b32 s20, 0xfffb0000
	s_mov_b32 s21, -1
	v_lshl_add_u64 v[132:133], v[182:183], 0, s[20:21]
	s_mov_b32 s20, 0x50000
	s_mov_b32 s21, 0
	v_lshl_add_u64 v[250:251], v[182:183], 0, s[20:21]
	global_load_dwordx4 v[128:131], v[132:133], off
	global_load_dwordx4 v[136:139], v[250:251], off offset:-1024
	global_load_dwordx4 v[132:135], v[182:183], off
	s_mov_b32 s20, 0xa0000
	v_lshl_add_u64 v[250:251], v[182:183], 0, s[20:21]
	global_load_dwordx4 v[140:143], v[250:251], off offset:-1024
.LBB0_265:
	ds_read_b64_tr_b16 v[216:217], v190 offset:0
	ds_read_b64_tr_b16 v[218:219], v190 offset:0x800
	ds_read_b64_tr_b16 v[220:221], v190 offset:0x1000
	ds_read_b64_tr_b16 v[222:223], v190 offset:0x1800
	ds_read_b64_tr_b16 v[224:225], v190 offset:0x2000
	ds_read_b64_tr_b16 v[226:227], v190 offset:0x2800
	ds_read_b64_tr_b16 v[228:229], v190 offset:0x3000
	ds_read_b64_tr_b16 v[230:231], v190 offset:0x3800
	s_waitcnt lgkmcnt(0)
	s_nop 0
	v_mfma_f32_32x32x16_bf16 v[0:15], v[160:163], v[216:219], v[0:15]
	ds_read_b64_tr_b16 v[216:217], v190 offset:0x200
	ds_read_b64_tr_b16 v[218:219], v190 offset:0xa00
	v_mfma_f32_32x32x16_bf16 v[0:15], v[164:167], v[220:223], v[0:15]
	ds_read_b64_tr_b16 v[220:221], v190 offset:0x1200
	ds_read_b64_tr_b16 v[222:223], v190 offset:0x1a00
	v_mfma_f32_32x32x16_bf16 v[0:15], v[168:171], v[224:227], v[0:15]
	ds_read_b64_tr_b16 v[224:225], v190 offset:0x2200
	ds_read_b64_tr_b16 v[226:227], v190 offset:0x2a00
	v_mfma_f32_32x32x16_bf16 v[0:15], v[172:175], v[228:231], v[0:15]
	ds_read_b64_tr_b16 v[228:229], v190 offset:0x3200
	ds_read_b64_tr_b16 v[230:231], v190 offset:0x3a00
	s_waitcnt lgkmcnt(0)
	v_mfma_f32_32x32x16_bf16 v[48:63], v[160:163], v[216:219], v[48:63]
	ds_read_b64_tr_b16 v[216:217], v190 offset:0x400
	ds_read_b64_tr_b16 v[218:219], v190 offset:0xc00
	v_mfma_f32_32x32x16_bf16 v[48:63], v[164:167], v[220:223], v[48:63]
	ds_read_b64_tr_b16 v[220:221], v190 offset:0x1400
	ds_read_b64_tr_b16 v[222:223], v190 offset:0x1c00
	v_mfma_f32_32x32x16_bf16 v[48:63], v[168:171], v[224:227], v[48:63]
	ds_read_b64_tr_b16 v[224:225], v190 offset:0x2400
	ds_read_b64_tr_b16 v[226:227], v190 offset:0x2c00
	v_mfma_f32_32x32x16_bf16 v[48:63], v[172:175], v[228:231], v[48:63]
	ds_read_b64_tr_b16 v[228:229], v190 offset:0x3400
	ds_read_b64_tr_b16 v[230:231], v190 offset:0x3c00
	s_waitcnt lgkmcnt(0)
	v_mfma_f32_32x32x16_bf16 v[32:47], v[160:163], v[216:219], v[32:47]
	ds_read_b64_tr_b16 v[216:217], v190 offset:0x600
	ds_read_b64_tr_b16 v[218:219], v190 offset:0xe00
	v_mfma_f32_32x32x16_bf16 v[32:47], v[164:167], v[220:223], v[32:47]
	ds_read_b64_tr_b16 v[220:221], v190 offset:0x1600
	ds_read_b64_tr_b16 v[222:223], v190 offset:0x1e00
	v_mfma_f32_32x32x16_bf16 v[32:47], v[168:171], v[224:227], v[32:47]
	ds_read_b64_tr_b16 v[224:225], v190 offset:0x2600
	ds_read_b64_tr_b16 v[226:227], v190 offset:0x2e00
	v_mfma_f32_32x32x16_bf16 v[32:47], v[172:175], v[228:231], v[32:47]
	ds_read_b64_tr_b16 v[228:229], v190 offset:0x3600
	ds_read_b64_tr_b16 v[230:231], v190 offset:0x3e00
	s_waitcnt lgkmcnt(0)
	v_mfma_f32_32x32x16_bf16 v[16:31], v[160:163], v[216:219], v[16:31]
	v_max_f32_e32 v160, v80, v81
	v_max3_f32 v160, v160, v82, v83
	v_max3_f32 v160, v160, v84, v85
	v_max3_f32 v160, v160, v86, v87
	v_max3_f32 v160, v160, v88, v89
	v_max3_f32 v160, v160, v90, v91
	v_max3_f32 v160, v160, v92, v93
	v_mfma_f32_32x32x16_bf16 v[16:31], v[164:167], v[220:223], v[16:31]
	v_max3_f32 v160, v160, v94, v95
	v_max3_f32 v160, v160, v64, v65
	v_max3_f32 v160, v160, v66, v67
	v_max3_f32 v160, v160, v68, v69
	v_max3_f32 v160, v160, v70, v71
	v_max3_f32 v160, v160, v72, v73
	v_max3_f32 v160, v160, v74, v75
	v_max3_f32 v160, v160, v76, v77
	v_mfma_f32_32x32x16_bf16 v[16:31], v[168:171], v[224:227], v[16:31]
	v_max3_f32 v160, v160, v78, v79
	v_mov_b32_e32 v161, v160
	s_nop 1
	v_permlane32_swap_b32_e32 v160, v161
	v_max_f32_e32 v160, v160, v161
	v_sub_f32_e32 v161, v160, v213
	v_cmp_ge_f32_e32 vcc, s71, v161
	v_max_f32_e32 v161, v213, v160
	v_mfma_f32_32x32x16_bf16 v[16:31], v[172:175], v[228:231], v[16:31]
	v_sub_f32_e32 v160, v213, v161
	v_mul_f32_e32 v160, 0x3e0293ee, v160
	v_exp_f32_e32 v160, v160
	s_cmp_eq_u64 vcc, exec
	s_cselect_b64 s[38:39], -1, 0
	s_barrier
	s_waitcnt vmcnt(4)
	v_cndmask_b32_e64 v160, v160, 1.0, s[38:39]
	v_cmp_gt_f32_e32 vcc, 1.0, v160
	s_cmp_lg_u64 s[42:43], 0
	s_cbranch_scc1 .Lkv2_lastw
	s_waitcnt vmcnt(7)
	v_mov_b64 v[218:219], v[144:145]
	v_mov_b64 v[220:221], v[146:147]
	s_waitcnt vmcnt(5)
	v_mov_b64 v[222:223], v[156:157]
	v_mov_b64 v[224:225], v[158:159]
	v_mov_b64 v[226:227], v[148:149]
	v_mov_b64 v[228:229], v[150:151]
	s_waitcnt vmcnt(4)
	v_mov_b64 v[230:231], v[152:153]
	v_mov_b64 v[232:233], v[154:155]
	s_branch .Lkv2_wdone
.Lkv2_lastw:
	s_waitcnt vmcnt(3)
	v_mov_b64 v[218:219], v[144:145]
	v_mov_b64 v[220:221], v[146:147]
	s_waitcnt vmcnt(1)
	v_mov_b64 v[222:223], v[156:157]
	v_mov_b64 v[224:225], v[158:159]
	v_mov_b64 v[226:227], v[148:149]
	v_mov_b64 v[228:229], v[150:151]
	s_waitcnt vmcnt(0)
	v_mov_b64 v[230:231], v[152:153]
	v_mov_b64 v[232:233], v[154:155]

; #define SWRITE(b, i) do { *(bf16x8*)(V_lds + (b) * SHM_V + vst0) = sr_[i].vs0;          \
;     *(bf16x8*)(V_lds + (b) * SHM_V + vst1) = sr_[i].vs1; int kc = sc * 2;               \
;     *(bf16x8*)(K_lds + (b) * SHM_K + KSWZ(sr, kc)) = sr_[i].ks0;                       \
;     *(bf16x8*)(K_lds + (b) * SHM_K + KSWZ(32 + sr, kc)) = sr_[i].ks1; } while (0)
; #define SWAIT() asm volatile("s_waitcnt vmcnt(4)" ::: "memory")
; #define RESC(a) do { if (__any((a) < 1.f)) { if (hi == 0) al_l[r32] = (a); asm volatile("s_waitcnt lgkmcnt(0)" ::: "memory"); \
;     for (int d = 0; d < 4; ++d) for (int r = 0; r < 16; ++r) o[d][r] *= al_l[crow(r, hi)]; } } while (0)
; __device__ __forceinline__ void partialSM(f32x16& p0, f32x16& p1, float& m_reg, float& mn, float& alpha) {
;     ...
;   if (__builtin_expect(__all(pmax - m_reg <= THR / SCALE), 1)) { mn = m_reg; alpha = 1.f; }
;   else { mn = fmaxf(m_reg, pmax); alpha = __builtin_amdgcn_exp2f((m_reg - mn) * C); m_reg = mn; }
;   float mnC = -mn * C;
;   for (int r = 0; r < 16; ++r) p0[r] = fmaf(p0[r], C, mnC); for (int r = 0; r < 16; ++r) p1[r] = fmaf(p1[r], C, mnC);
;   for (int r = 0; r < 16; ++r) p0[r] = __builtin_amdgcn_exp2f(p0[r]);
; __device__ __forceinline__ void attn_body(const bf16_t* Qb, const bf16_t* Kh, const bf16_t* Vh, const bf16_t* Gb, bf16_t* Ob, int seq, char* lds,
;                                           const float* qgain, const float* cosA, const float* sinA, int t0) {
;     ...
;     pv_d0(o, vb0 + (int)SHM_V, pa0, pa1, pa2, pa3); partialSM(pA0, pA1, m_reg, mnA, alA);
;     __syncthreads(); SWAIT(); SWRITE(1, SO);
;     RESC(alA); __syncthreads();
.LBB0_269:
	v_cndmask_b32_e64 v164, v161, v213, s[38:39]
	v_mul_f32_e32 v150, 0xbe0293ee, v164
	v_mov_b32_e32 v151, v150
	v_fmamk_f32 v80, v80, 0x3e0293ee, v150
	v_fmamk_f32 v81, v81, 0x3e0293ee, v150
	v_fmamk_f32 v82, v82, 0x3e0293ee, v150
	v_fmamk_f32 v83, v83, 0x3e0293ee, v150
	v_fmamk_f32 v84, v84, 0x3e0293ee, v150
	v_fmamk_f32 v85, v85, 0x3e0293ee, v150
	v_fmamk_f32 v86, v86, 0x3e0293ee, v150
	v_fmamk_f32 v87, v87, 0x3e0293ee, v150
	v_fmamk_f32 v88, v88, 0x3e0293ee, v150
	v_fmamk_f32 v89, v89, 0x3e0293ee, v150
	v_fmamk_f32 v90, v90, 0x3e0293ee, v150
	v_fmamk_f32 v91, v91, 0x3e0293ee, v150
	v_fmamk_f32 v92, v92, 0x3e0293ee, v150
	v_fmamk_f32 v93, v93, 0x3e0293ee, v150
	v_fmamk_f32 v94, v94, 0x3e0293ee, v150
	v_fmac_f32_e32 v151, 0x3e0293ee, v95
	v_exp_f32_e32 v175, v80
	v_exp_f32_e32 v216, v81
	v_exp_f32_e32 v161, v82
	v_exp_f32_e32 v213, v83
	v_exp_f32_e32 v162, v84
	v_exp_f32_e32 v174, v85
	v_exp_f32_e32 v163, v86
	v_exp_f32_e32 v173, v87
	v_exp_f32_e32 v170, v88
	v_exp_f32_e32 v172, v89
	v_exp_f32_e32 v169, v90
	v_exp_f32_e32 v171, v91
	v_exp_f32_e32 v166, v92
	v_exp_f32_e32 v168, v93
	v_exp_f32_e32 v165, v94
	v_exp_f32_e32 v167, v151
	v_pk_fma_f32 v[156:157], v[64:65], s[62:63], v[150:151] op_sel_hi:[1,0,0]
	v_add_f32_e32 v64, v210, v211
	v_fmac_f32_e32 v64, v209, v189
	v_add_f32_e32 v189, v214, v215
	s_mov_b64 s[20:21], 0x140000
	v_pk_fma_f32 v[154:155], v[66:67], s[62:63], v[150:151] op_sel_hi:[1,0,0]
	v_pk_fma_f32 v[148:149], v[68:69], s[62:63], v[150:151] op_sel_hi:[1,0,0]
	v_pk_fma_f32 v[146:147], v[70:71], s[62:63], v[150:151] op_sel_hi:[1,0,0]
	v_pk_fma_f32 v[144:145], v[72:73], s[62:63], v[150:151] op_sel_hi:[1,0,0]
	v_pk_fma_f32 v[158:159], v[74:75], s[62:63], v[150:151] op_sel_hi:[1,0,0]
	v_pk_fma_f32 v[152:153], v[76:77], s[62:63], v[150:151] op_sel_hi:[1,0,0]
	v_pk_fma_f32 v[150:151], v[78:79], s[62:63], v[150:151] op_sel_hi:[1,0,0]
	v_fmac_f32_e32 v189, v64, v212
	v_lshl_add_u64 v[182:183], v[182:183], 0, s[20:21]
	s_and_b64 vcc, exec, s[42:43]
	s_waitcnt lgkmcnt(0)
	s_barrier
	ds_write_b128 v192, v[218:221] offset:16384
	ds_write_b128 v193, v[222:225] offset:16384
	ds_write_b128 v199, v[226:229] offset:32768
	ds_write_b128 v200, v[230:233] offset:32768
	s_cbranch_vccnz .LBB0_271
	v_mov_b32_e32 v209, v160
	s_branch .LBB0_259

; #define SBAR() __builtin_amdgcn_sched_barrier(0)
; __device__ __forceinline__ void partialSM(f32x16& p0, f32x16& p1, float& m_reg, float& mn, float& alpha) {
;     ...
;   for (int r = 0; r < 16; ++r) p0[r] = fmaf(p0[r], C, mnC); for (int r = 0; r < 16; ++r) p1[r] = fmaf(p1[r], C, mnC);
;   for (int r = 0; r < 16; ++r) p0[r] = __builtin_amdgcn_exp2f(p0[r]);
; }
; __device__ __forceinline__ void finishSM(f32x16& p0, f32x16& p1, float alpha, float& l_reg, bf16x8& pa0, bf16x8& pa1, bf16x8& pa2, bf16x8& pa3) {
;   for (int r = 0; r < 16; ++r) p1[r] = __builtin_amdgcn_exp2f(p1[r]);
;   float ps = 0; for (int r = 0; r < 16; ++r) ps += p0[r]; for (int r = 0; r < 16; ++r) ps += p1[r];
;   { auto rr = __builtin_amdgcn_permlane32_swap(__float_as_uint(ps), __float_as_uint(ps), false, false);
;     ps = __uint_as_float(rr[0]) + __uint_as_float(rr[1]); }
;   l_reg = l_reg * alpha + ps;
;     ...
;   PK4(p0, 0, pa0); PK4(p0, 8, pa1); PK4(p1, 0, pa2); PK4(p1, 8, pa3);
; template <int D0> __device__ __forceinline__ void pv_one(f32x16& od, int vb, bf16x8 pa0, bf16x8 pa1, bf16x8 pa2, bf16x8 pa3) {
;   const s16x4 l0 = tr_read<v_rd_off(D0, 0, 0)>(vb), h0 = tr_read<v_rd_off(D0, 0, 1)>(vb), l1 = tr_read<v_rd_off(D0, 1, 0)>(vb), h1 = tr_read<v_rd_off(D0, 1, 1)>(vb);
;   const s16x4 l2 = tr_read<v_rd_off(D0, 2, 0)>(vb), h2 = tr_read<v_rd_off(D0, 2, 1)>(vb), l3 = tr_read<v_rd_off(D0, 3, 0)>(vb), h3 = tr_read<v_rd_off(D0, 3, 1)>(vb);
;   asm volatile("s_waitcnt lgkmcnt(0)" ::: "memory"); SBAR();
;     ...
;   od = __builtin_amdgcn_mfma_f32_32x32x16_bf16(pa0, PK(l0, h0), od, 0, 0, 0);
;   od = __builtin_amdgcn_mfma_f32_32x32x16_bf16(pa1, PK(l1, h1), od, 0, 0, 0);
;   od = __builtin_amdgcn_mfma_f32_32x32x16_bf16(pa2, PK(l2, h2), od, 0, 0, 0);
;   od = __builtin_amdgcn_mfma_f32_32x32x16_bf16(pa3, PK(l3, h3), od, 0, 0, 0);
;     ...
; }
; __device__ __forceinline__ void pv_d0(f32x16* o, int vb, bf16x8 pa0, bf16x8 pa1, bf16x8 pa2, bf16x8 pa3) {
;   pv_one<0>(o[0], vb, pa0, pa1, pa2, pa3); pv_one<1>(o[1], vb, pa0, pa1, pa2, pa3); pv_one<2>(o[2], vb, pa0, pa1, pa2, pa3); pv_one<3>(o[3], vb, pa0, pa1, pa2, pa3);
.LBB0_275:
	v_cndmask_b32_e64 v97, v97, v164, s[38:39]
	v_mul_f32_e32 v97, 0xbe0293ee, v97
	v_fmamk_f32 v80, v80, 0x3e0293ee, v97
	v_fmamk_f32 v81, v81, 0x3e0293ee, v97
	v_fmamk_f32 v98, v82, 0x3e0293ee, v97
	v_exp_f32_e32 v82, v80
	v_fmamk_f32 v99, v84, 0x3e0293ee, v97
	v_exp_f32_e32 v84, v81
	v_fmamk_f32 v83, v83, 0x3e0293ee, v97
	v_exp_f32_e32 v80, v98
	v_fmamk_f32 v64, v64, 0x3e0293ee, v97
	v_exp_f32_e32 v83, v83
	v_fmamk_f32 v102, v85, 0x3e0293ee, v97
	v_fmamk_f32 v111, v94, 0x3e0293ee, v97
	v_fmamk_f32 v94, v75, 0x3e0293ee, v97
	v_exp_f32_e32 v75, v99
	v_exp_f32_e32 v98, v64
	v_add_f32_e32 v64, 0, v82
	v_fmamk_f32 v103, v86, 0x3e0293ee, v97
	v_exp_f32_e32 v81, v102
	v_add_f32_e32 v64, v84, v64
	v_fmamk_f32 v104, v87, 0x3e0293ee, v97
	v_fmamk_f32 v110, v93, 0x3e0293ee, v97
	v_fmamk_f32 v93, v74, 0x3e0293ee, v97
	v_exp_f32_e32 v74, v103
	v_add_f32_e32 v64, v80, v64
	v_fmamk_f32 v105, v88, 0x3e0293ee, v97
	v_fmamk_f32 v112, v95, 0x3e0293ee, v97
	v_fmamk_f32 v95, v76, 0x3e0293ee, v97
	v_exp_f32_e32 v76, v104
	v_add_f32_e32 v64, v83, v64
	v_fmamk_f32 v106, v89, 0x3e0293ee, v97
	v_fmamk_f32 v107, v90, 0x3e0293ee, v97
	v_fmamk_f32 v90, v71, 0x3e0293ee, v97
	v_exp_f32_e32 v71, v105
	v_add_f32_e32 v64, v75, v64
	v_fmamk_f32 v109, v92, 0x3e0293ee, v97
	v_fmamk_f32 v92, v73, 0x3e0293ee, v97
	v_exp_f32_e32 v73, v106
	v_add_f32_e32 v64, v81, v64
	v_fmamk_f32 v108, v91, 0x3e0293ee, v97
	v_fmamk_f32 v88, v69, 0x3e0293ee, v97
	v_exp_f32_e32 v69, v107
	v_add_f32_e32 v64, v74, v64
	v_fmamk_f32 v91, v72, 0x3e0293ee, v97
	v_exp_f32_e32 v72, v108
	v_add_f32_e32 v64, v76, v64
	v_fmamk_f32 v86, v67, 0x3e0293ee, v97
	v_exp_f32_e32 v67, v109
	v_add_f32_e32 v64, v71, v64
	v_fmamk_f32 v89, v70, 0x3e0293ee, v97
	v_exp_f32_e32 v70, v110
	v_add_f32_e32 v64, v73, v64
	v_fmamk_f32 v85, v66, 0x3e0293ee, v97
	v_exp_f32_e32 v66, v111
	v_add_f32_e32 v64, v69, v64
	v_fmamk_f32 v87, v68, 0x3e0293ee, v97
	v_exp_f32_e32 v68, v112
	v_add_f32_e32 v64, v72, v64
	v_fmamk_f32 v65, v65, 0x3e0293ee, v97
	v_add_f32_e32 v64, v67, v64
	v_exp_f32_e32 v99, v65
	v_add_f32_e32 v64, v70, v64
	v_exp_f32_e32 v85, v85
	v_add_f32_e32 v64, v66, v64
	v_exp_f32_e32 v86, v86
	v_add_f32_e32 v64, v68, v64
	v_exp_f32_e32 v87, v87
	v_add_f32_e32 v64, v98, v64
	v_exp_f32_e32 v88, v88
	v_add_f32_e32 v64, v99, v64
	v_exp_f32_e32 v89, v89
	v_add_f32_e32 v64, v85, v64
	v_exp_f32_e32 v90, v90
	v_add_f32_e32 v64, v86, v64
	v_exp_f32_e32 v91, v91
	v_add_f32_e32 v64, v87, v64
	v_exp_f32_e32 v92, v92
	v_add_f32_e32 v64, v88, v64
	v_exp_f32_e32 v93, v93
	v_add_f32_e32 v64, v89, v64
	v_exp_f32_e32 v94, v94
	v_add_f32_e32 v64, v90, v64
	v_fmamk_f32 v77, v77, 0x3e0293ee, v97
	v_exp_f32_e32 v95, v95
	v_add_f32_e32 v64, v91, v64
	v_fmamk_f32 v78, v78, 0x3e0293ee, v97
	v_exp_f32_e32 v102, v77
	v_add_f32_e32 v64, v92, v64
	v_fmac_f32_e32 v97, 0x3e0293ee, v79
	v_exp_f32_e32 v103, v78
	v_add_f32_e32 v64, v93, v64
	v_exp_f32_e32 v97, v97
	v_add_f32_e32 v64, v94, v64
	v_add_f32_e32 v64, v95, v64
	v_add_f32_e32 v64, v102, v64
	v_add_f32_e32 v64, v103, v64
	v_add_f32_e32 v64, v97, v64
	v_mov_b32_e32 v65, v64
	s_nop 1
	v_permlane32_swap_b32_e32 v64, v65
	v_cvt_pk_bf16_f32 v78, v82, v84
	v_cvt_pk_bf16_f32 v79, v80, v83
	v_cvt_pk_bf16_f32 v80, v75, v81
	v_cvt_pk_bf16_f32 v81, v74, v76
	v_cvt_pk_bf16_f32 v74, v71, v73
	v_cvt_pk_bf16_f32 v75, v69, v72
	v_cvt_pk_bf16_f32 v76, v67, v70
	v_cvt_pk_bf16_f32 v77, v66, v68
	v_cvt_pk_bf16_f32 v66, v98, v99
	v_cvt_pk_bf16_f32 v67, v85, v86
	v_cvt_pk_bf16_f32 v68, v87, v88
	v_cvt_pk_bf16_f32 v69, v89, v90
	v_cvt_pk_bf16_f32 v70, v91, v92
	v_cvt_pk_bf16_f32 v71, v93, v94
	v_cvt_pk_bf16_f32 v72, v95, v102
	v_cvt_pk_bf16_f32 v73, v103, v97
	s_nop 0
	v_permlane32_swap_b32_e32 v78, v80
	v_permlane32_swap_b32_e32 v79, v81
	v_permlane32_swap_b32_e32 v74, v76
	v_permlane32_swap_b32_e32 v75, v77
	v_permlane32_swap_b32_e32 v66, v68
	v_permlane32_swap_b32_e32 v67, v69
	v_permlane32_swap_b32_e32 v70, v72
	v_permlane32_swap_b32_e32 v71, v73
	v_readfirstlane_b32 s20, v252
	s_cmp_ge_u32 s20, 0x100
	s_cbranch_scc1 .Lpp_exit_skip
	s_barrier
.Lpp_exit_skip:
	ds_read_b64_tr_b16 v[82:83], v190 offset:0
	ds_read_b64_tr_b16 v[84:85], v190 offset:0x800
	ds_read_b64_tr_b16 v[86:87], v190 offset:0x1000
	ds_read_b64_tr_b16 v[88:89], v190 offset:0x1800
	ds_read_b64_tr_b16 v[90:91], v190 offset:0x2000
	ds_read_b64_tr_b16 v[92:93], v190 offset:0x2800
	ds_read_b64_tr_b16 v[102:103], v190 offset:0x3000
	ds_read_b64_tr_b16 v[104:105], v190 offset:0x3800
	s_waitcnt lgkmcnt(0)
	s_nop 0
	v_mfma_f32_32x32x16_bf16 v[0:15], v[78:81], v[82:85], v[0:15]
	ds_read_b64_tr_b16 v[82:83], v190 offset:0x200
	ds_read_b64_tr_b16 v[84:85], v190 offset:0xa00
	v_mfma_f32_32x32x16_bf16 v[0:15], v[74:77], v[86:89], v[0:15]
	ds_read_b64_tr_b16 v[86:87], v190 offset:0x1200
	ds_read_b64_tr_b16 v[88:89], v190 offset:0x1a00
	v_mfma_f32_32x32x16_bf16 v[0:15], v[66:69], v[90:93], v[0:15]
	ds_read_b64_tr_b16 v[90:91], v190 offset:0x2200
	ds_read_b64_tr_b16 v[92:93], v190 offset:0x2a00
	v_mfma_f32_32x32x16_bf16 v[0:15], v[70:73], v[102:105], v[0:15]
	ds_read_b64_tr_b16 v[102:103], v190 offset:0x3200
	ds_read_b64_tr_b16 v[104:105], v190 offset:0x3a00
	s_waitcnt lgkmcnt(0)
	v_mfma_f32_32x32x16_bf16 v[48:63], v[78:81], v[82:85], v[48:63]
	ds_read_b64_tr_b16 v[82:83], v190 offset:0x400
	ds_read_b64_tr_b16 v[84:85], v190 offset:0xc00
	v_mfma_f32_32x32x16_bf16 v[48:63], v[74:77], v[86:89], v[48:63]
	ds_read_b64_tr_b16 v[86:87], v190 offset:0x1400
	ds_read_b64_tr_b16 v[88:89], v190 offset:0x1c00
	v_mfma_f32_32x32x16_bf16 v[48:63], v[66:69], v[90:93], v[48:63]
	ds_read_b64_tr_b16 v[90:91], v190 offset:0x2400
	ds_read_b64_tr_b16 v[92:93], v190 offset:0x2c00
	v_mfma_f32_32x32x16_bf16 v[48:63], v[70:73], v[102:105], v[48:63]
	ds_read_b64_tr_b16 v[102:103], v190 offset:0x3400
	ds_read_b64_tr_b16 v[104:105], v190 offset:0x3c00
	s_waitcnt lgkmcnt(0)
	v_mfma_f32_32x32x16_bf16 v[32:47], v[78:81], v[82:85], v[32:47]
	ds_read_b64_tr_b16 v[82:83], v190 offset:0x600
	ds_read_b64_tr_b16 v[84:85], v190 offset:0xe00
	v_mfma_f32_32x32x16_bf16 v[32:47], v[74:77], v[86:89], v[32:47]
	ds_read_b64_tr_b16 v[86:87], v190 offset:0x1600
	ds_read_b64_tr_b16 v[88:89], v190 offset:0x1e00
	v_mfma_f32_32x32x16_bf16 v[32:47], v[66:69], v[90:93], v[32:47]
	ds_read_b64_tr_b16 v[90:91], v190 offset:0x2600
	ds_read_b64_tr_b16 v[92:93], v190 offset:0x2e00
	v_mfma_f32_32x32x16_bf16 v[32:47], v[70:73], v[102:105], v[32:47]
	ds_read_b64_tr_b16 v[102:103], v190 offset:0x3600
	ds_read_b64_tr_b16 v[104:105], v190 offset:0x3e00
	s_waitcnt lgkmcnt(0)
	v_mfma_f32_32x32x16_bf16 v[16:31], v[78:81], v[82:85], v[16:31]
	v_mfma_f32_32x32x16_bf16 v[16:31], v[74:77], v[86:89], v[16:31]
	v_mfma_f32_32x32x16_bf16 v[16:31], v[66:69], v[90:93], v[16:31]
	v_mfma_f32_32x32x16_bf16 v[16:31], v[70:73], v[102:105], v[16:31]
	s_and_saveexec_b64 s[38:39], s[36:37]
	s_cbranch_execz .LBB0_257
	v_add_f32_e32 v66, v100, v101
	v_fmac_f32_e32 v66, v189, v160
	v_add_f32_e32 v64, v64, v65
	v_fmac_f32_e32 v64, v66, v96
	ds_write_b32 v188, v64
	s_branch .LBB0_257
